# v033 + GEMM accumulator zeroing with v_mov_b64 (64 instead of 128 VALU per unit)
# speedup vs baseline: 1.0023x; 1.0023x over previous
; template <class Epi, class Sched, bool ALIGN_EPI = false, bool SP2 = false>
; __device__ __forceinline__ void gemm_phase(PG8_LAS unsigned char* lds, const Gemm g, const Sched& S, const Epi& E, int tid_in) {
;     ...
;         for (int t = 0; t < nt; t += 2) {
;             const bool last = (t == nt - 2);
;             const char* a1 = cA + (size_t)(t + 1) * kstep;
;             const char* a2 = last ? nA : cA + (size_t)(t + 2) * kstep; const char* b2 = last ? nB : cB + (size_t)(t + 2) * kstep;
;     ...
;         if (!Epi::DUAL || cur.sel == 1) {
; #pragma unroll
;         for (int a = 0; a < 2; ++a)
; #pragma unroll
;             for (int b = 0; b < 2; ++b)
; #pragma unroll
;                 for (int m = 0; m < 4; ++m)
; #pragma unroll
;                     for (int n = 0; n < 2; ++n) acc[a][b][m][n] = (f32x4){0.f, 0.f, 0.f, 0.f};
;         }
;         cur = nxt; cA = nA; cB = nB; ++ui;
.LBB0_285:
	v_mov_b64_e32 v[0:1], 0
	v_mov_b64_e32 v[2:3], 0
	v_mov_b64_e32 v[4:5], 0
	v_mov_b64_e32 v[6:7], 0
	v_mov_b64_e32 v[8:9], 0
	v_mov_b64_e32 v[10:11], 0
	v_mov_b64_e32 v[12:13], 0
	v_mov_b64_e32 v[14:15], 0
	v_mov_b64_e32 v[16:17], 0
	v_mov_b64_e32 v[18:19], 0
	v_mov_b64_e32 v[20:21], 0
	v_mov_b64_e32 v[22:23], 0
	v_mov_b64_e32 v[24:25], 0
	v_mov_b64_e32 v[26:27], 0
	v_mov_b64_e32 v[28:29], 0
	v_mov_b64_e32 v[30:31], 0
	v_mov_b64_e32 v[32:33], 0
	v_mov_b64_e32 v[34:35], 0
	v_mov_b64_e32 v[36:37], 0
	v_mov_b64_e32 v[38:39], 0
	v_mov_b64_e32 v[40:41], 0
	v_mov_b64_e32 v[42:43], 0
	v_mov_b64_e32 v[44:45], 0
	v_mov_b64_e32 v[46:47], 0
	v_mov_b64_e32 v[48:49], 0
	v_mov_b64_e32 v[50:51], 0
	v_mov_b64_e32 v[52:53], 0
	v_mov_b64_e32 v[54:55], 0
	v_mov_b64_e32 v[56:57], 0
	v_mov_b64_e32 v[58:59], 0
	v_mov_b64_e32 v[60:61], 0
	v_mov_b64_e32 v[62:63], 0
	v_mov_b64_e32 v[64:65], 0
	v_mov_b64_e32 v[66:67], 0
	v_mov_b64_e32 v[68:69], 0
	v_mov_b64_e32 v[70:71], 0
	v_mov_b64_e32 v[72:73], 0
	v_mov_b64_e32 v[74:75], 0
	v_mov_b64_e32 v[76:77], 0
	v_mov_b64_e32 v[78:79], 0
	v_mov_b64_e32 v[80:81], 0
	v_mov_b64_e32 v[82:83], 0
	v_mov_b64_e32 v[84:85], 0
	v_mov_b64_e32 v[86:87], 0
	v_mov_b64_e32 v[88:89], 0
	v_mov_b64_e32 v[90:91], 0
	v_mov_b64_e32 v[92:93], 0
	v_mov_b64_e32 v[94:95], 0
	v_mov_b64_e32 v[96:97], 0
	v_mov_b64_e32 v[98:99], 0
	v_mov_b64_e32 v[100:101], 0
	v_mov_b64_e32 v[102:103], 0
	v_mov_b64_e32 v[104:105], 0
	v_mov_b64_e32 v[106:107], 0
	v_mov_b64_e32 v[108:109], 0
	v_mov_b64_e32 v[110:111], 0
	v_mov_b64_e32 v[112:113], 0
	v_mov_b64_e32 v[114:115], 0
	v_mov_b64_e32 v[116:117], 0
	v_mov_b64_e32 v[118:119], 0
	v_mov_b64_e32 v[120:121], 0
	v_mov_b64_e32 v[122:123], 0
	v_mov_b64_e32 v[124:125], 0
	v_mov_b64_e32 v[126:127], 0
	s_andn2_b64 vcc, exec, s[38:39]
	s_cbranch_vccnz .LBB0_288
	s_add_u32 s6, s10, 0x80
	s_addc_u32 s7, s11, 0
	s_add_u32 s1, s8, 0x100
	v_mov_b32_e32 v0, 0
	s_addc_u32 s2, s9, 0
	s_mov_b32 s3, 0
	v_mov_b32_e32 v1, v0
	v_mov_b32_e32 v2, v0
	v_mov_b32_e32 v3, v0
	v_mov_b32_e32 v4, v0
	v_mov_b32_e32 v5, v0
	v_mov_b32_e32 v6, v0
	v_mov_b32_e32 v7, v0
	v_mov_b32_e32 v16, v0
	v_mov_b32_e32 v17, v0
	v_mov_b32_e32 v18, v0
	v_mov_b32_e32 v19, v0
	v_mov_b32_e32 v20, v0
	v_mov_b32_e32 v21, v0
	v_mov_b32_e32 v22, v0
	v_mov_b32_e32 v23, v0
	v_mov_b32_e32 v32, v0
	v_mov_b32_e32 v33, v0
	v_mov_b32_e32 v34, v0
	v_mov_b32_e32 v35, v0
	v_mov_b32_e32 v36, v0
	v_mov_b32_e32 v37, v0
	v_mov_b32_e32 v38, v0
	v_mov_b32_e32 v39, v0
	v_mov_b32_e32 v48, v0
	v_mov_b32_e32 v49, v0
	v_mov_b32_e32 v50, v0
	v_mov_b32_e32 v51, v0
	v_mov_b32_e32 v52, v0
	v_mov_b32_e32 v53, v0
	v_mov_b32_e32 v54, v0
	v_mov_b32_e32 v55, v0
	v_mov_b32_e32 v8, v0
	v_mov_b32_e32 v9, v0
	v_mov_b32_e32 v10, v0
	v_mov_b32_e32 v11, v0
	v_mov_b32_e32 v12, v0
	v_mov_b32_e32 v13, v0
	v_mov_b32_e32 v14, v0
	v_mov_b32_e32 v15, v0
	v_mov_b32_e32 v24, v0
	v_mov_b32_e32 v25, v0
	v_mov_b32_e32 v26, v0
	v_mov_b32_e32 v27, v0
	v_mov_b32_e32 v28, v0
	v_mov_b32_e32 v29, v0
	v_mov_b32_e32 v30, v0
	v_mov_b32_e32 v31, v0
	v_mov_b32_e32 v40, v0
	v_mov_b32_e32 v41, v0
	v_mov_b32_e32 v42, v0
	v_mov_b32_e32 v43, v0
	v_mov_b32_e32 v44, v0
	v_mov_b32_e32 v45, v0
	v_mov_b32_e32 v46, v0
	v_mov_b32_e32 v47, v0
	v_mov_b32_e32 v56, v0
	v_mov_b32_e32 v57, v0
	v_mov_b32_e32 v58, v0
	v_mov_b32_e32 v59, v0
	v_mov_b32_e32 v60, v0
	v_mov_b32_e32 v61, v0
	v_mov_b32_e32 v62, v0
	v_mov_b32_e32 v63, v0
	v_mov_b32_e32 v64, v0
	v_mov_b32_e32 v65, v0
	v_mov_b32_e32 v66, v0
	v_mov_b32_e32 v67, v0
	v_mov_b32_e32 v68, v0
	v_mov_b32_e32 v69, v0
	v_mov_b32_e32 v70, v0
	v_mov_b32_e32 v71, v0
	v_mov_b32_e32 v80, v0
	v_mov_b32_e32 v81, v0
	v_mov_b32_e32 v82, v0
	v_mov_b32_e32 v83, v0
	v_mov_b32_e32 v84, v0
	v_mov_b32_e32 v85, v0
	v_mov_b32_e32 v86, v0
	v_mov_b32_e32 v87, v0
	v_mov_b32_e32 v96, v0
	v_mov_b32_e32 v97, v0
	v_mov_b32_e32 v98, v0
	v_mov_b32_e32 v99, v0
	v_mov_b32_e32 v100, v0
	v_mov_b32_e32 v101, v0
	v_mov_b32_e32 v102, v0
	v_mov_b32_e32 v103, v0
	v_mov_b32_e32 v112, v0
	v_mov_b32_e32 v113, v0
	v_mov_b32_e32 v114, v0
	v_mov_b32_e32 v115, v0
	v_mov_b32_e32 v116, v0
	v_mov_b32_e32 v117, v0
	v_mov_b32_e32 v118, v0
	v_mov_b32_e32 v119, v0
	v_mov_b32_e32 v72, v0
	v_mov_b32_e32 v73, v0
	v_mov_b32_e32 v74, v0
	v_mov_b32_e32 v75, v0
	v_mov_b32_e32 v76, v0
	v_mov_b32_e32 v77, v0
	v_mov_b32_e32 v78, v0
	v_mov_b32_e32 v79, v0
	v_mov_b32_e32 v88, v0
	v_mov_b32_e32 v89, v0
	v_mov_b32_e32 v90, v0
	v_mov_b32_e32 v91, v0
	v_mov_b32_e32 v92, v0
	v_mov_b32_e32 v93, v0
	v_mov_b32_e32 v94, v0
	v_mov_b32_e32 v95, v0
	v_mov_b32_e32 v104, v0
	v_mov_b32_e32 v105, v0
	v_mov_b32_e32 v106, v0
	v_mov_b32_e32 v107, v0
	v_mov_b32_e32 v108, v0
	v_mov_b32_e32 v109, v0
	v_mov_b32_e32 v110, v0
	v_mov_b32_e32 v111, v0
	v_mov_b32_e32 v120, v0
	v_mov_b32_e32 v121, v0
	v_mov_b32_e32 v122, v0
	v_mov_b32_e32 v123, v0
	v_mov_b32_e32 v124, v0
	v_mov_b32_e32 v125, v0
	v_mov_b32_e32 v126, v0
	v_mov_b32_e32 v127, v0

; template <class Epi, class Sched, bool ALIGN_EPI = false, bool SP2 = false>
; __device__ __forceinline__ void gemm_phase(PG8_LAS unsigned char* lds, const Gemm g, const Sched& S, const Epi& E, int tid_in) {
;     ...
;         for (int t = 0; t < nt; t += 2) {
;             const bool last = (t == nt - 2);
;             const char* a1 = cA + (size_t)(t + 1) * kstep;
;             const char* a2 = last ? nA : cA + (size_t)(t + 2) * kstep; const char* b2 = last ? nB : cB + (size_t)(t + 2) * kstep;
;     ...
;         if (!Epi::DUAL || cur.sel == 1) {
; #pragma unroll
;         for (int a = 0; a < 2; ++a)
; #pragma unroll
;             for (int b = 0; b < 2; ++b)
; #pragma unroll
;                 for (int m = 0; m < 4; ++m)
; #pragma unroll
;                     for (int n = 0; n < 2; ++n) acc[a][b][m][n] = (f32x4){0.f, 0.f, 0.f, 0.f};
;         }
;         cur = nxt; cA = nA; cB = nB; ++ui;
.LBB0_496:
	v_mov_b64_e32 v[0:1], 0
	v_mov_b64_e32 v[2:3], 0
	v_mov_b64_e32 v[4:5], 0
	v_mov_b64_e32 v[6:7], 0
	v_mov_b64_e32 v[8:9], 0
	v_mov_b64_e32 v[10:11], 0
	v_mov_b64_e32 v[12:13], 0
	v_mov_b64_e32 v[14:15], 0
	v_mov_b64_e32 v[16:17], 0
	v_mov_b64_e32 v[18:19], 0
	v_mov_b64_e32 v[20:21], 0
	v_mov_b64_e32 v[22:23], 0
	v_mov_b64_e32 v[24:25], 0
	v_mov_b64_e32 v[26:27], 0
	v_mov_b64_e32 v[28:29], 0
	v_mov_b64_e32 v[30:31], 0
	v_mov_b64_e32 v[32:33], 0
	v_mov_b64_e32 v[34:35], 0
	v_mov_b64_e32 v[36:37], 0
	v_mov_b64_e32 v[38:39], 0
	v_mov_b64_e32 v[40:41], 0
	v_mov_b64_e32 v[42:43], 0
	v_mov_b64_e32 v[44:45], 0
	v_mov_b64_e32 v[46:47], 0
	v_mov_b64_e32 v[48:49], 0
	v_mov_b64_e32 v[50:51], 0
	v_mov_b64_e32 v[52:53], 0
	v_mov_b64_e32 v[54:55], 0
	v_mov_b64_e32 v[56:57], 0
	v_mov_b64_e32 v[58:59], 0
	v_mov_b64_e32 v[60:61], 0
	v_mov_b64_e32 v[62:63], 0
	v_mov_b64_e32 v[64:65], 0
	v_mov_b64_e32 v[66:67], 0
	v_mov_b64_e32 v[68:69], 0
	v_mov_b64_e32 v[70:71], 0
	v_mov_b64_e32 v[72:73], 0
	v_mov_b64_e32 v[74:75], 0
	v_mov_b64_e32 v[76:77], 0
	v_mov_b64_e32 v[78:79], 0
	v_mov_b64_e32 v[80:81], 0
	v_mov_b64_e32 v[82:83], 0
	v_mov_b64_e32 v[84:85], 0
	v_mov_b64_e32 v[86:87], 0
	v_mov_b64_e32 v[88:89], 0
	v_mov_b64_e32 v[90:91], 0
	v_mov_b64_e32 v[92:93], 0
	v_mov_b64_e32 v[94:95], 0
	v_mov_b64_e32 v[96:97], 0
	v_mov_b64_e32 v[98:99], 0
	v_mov_b64_e32 v[100:101], 0
	v_mov_b64_e32 v[102:103], 0
	v_mov_b64_e32 v[104:105], 0
	v_mov_b64_e32 v[106:107], 0
	v_mov_b64_e32 v[108:109], 0
	v_mov_b64_e32 v[110:111], 0
	v_mov_b64_e32 v[112:113], 0
	v_mov_b64_e32 v[114:115], 0
	v_mov_b64_e32 v[116:117], 0
	v_mov_b64_e32 v[118:119], 0
	v_mov_b64_e32 v[120:121], 0
	v_mov_b64_e32 v[122:123], 0
	v_mov_b64_e32 v[124:125], 0
	v_mov_b64_e32 v[126:127], 0
	s_andn2_b64 vcc, exec, s[20:21]
	s_cbranch_vccnz .LBB0_499
	s_add_u32 s26, s26, 0x80
	s_addc_u32 s27, s27, 0
	s_add_u32 s50, s28, 0x100
	v_mov_b32_e32 v0, 0
	s_addc_u32 s51, s29, 0
	s_mov_b32 s28, 0
	v_mov_b32_e32 v1, v0
	v_mov_b32_e32 v2, v0
	v_mov_b32_e32 v3, v0
	v_mov_b32_e32 v4, v0
	v_mov_b32_e32 v5, v0
	v_mov_b32_e32 v6, v0
	v_mov_b32_e32 v7, v0
	v_mov_b32_e32 v8, v0
	v_mov_b32_e32 v9, v0
	v_mov_b32_e32 v10, v0
	v_mov_b32_e32 v11, v0
	v_mov_b32_e32 v12, v0
	v_mov_b32_e32 v13, v0
	v_mov_b32_e32 v14, v0
	v_mov_b32_e32 v15, v0
	v_mov_b32_e32 v16, v0
	v_mov_b32_e32 v17, v0
	v_mov_b32_e32 v18, v0
	v_mov_b32_e32 v19, v0
	v_mov_b32_e32 v20, v0
	v_mov_b32_e32 v21, v0
	v_mov_b32_e32 v22, v0
	v_mov_b32_e32 v23, v0
	v_mov_b32_e32 v24, v0
	v_mov_b32_e32 v25, v0
	v_mov_b32_e32 v26, v0
	v_mov_b32_e32 v27, v0
	v_mov_b32_e32 v28, v0
	v_mov_b32_e32 v29, v0
	v_mov_b32_e32 v30, v0
	v_mov_b32_e32 v31, v0
	v_mov_b32_e32 v64, v0
	v_mov_b32_e32 v65, v0
	v_mov_b32_e32 v66, v0
	v_mov_b32_e32 v67, v0
	v_mov_b32_e32 v68, v0
	v_mov_b32_e32 v69, v0
	v_mov_b32_e32 v70, v0
	v_mov_b32_e32 v71, v0
	v_mov_b32_e32 v72, v0
	v_mov_b32_e32 v73, v0
	v_mov_b32_e32 v74, v0
	v_mov_b32_e32 v75, v0
	v_mov_b32_e32 v76, v0
	v_mov_b32_e32 v77, v0
	v_mov_b32_e32 v78, v0
	v_mov_b32_e32 v79, v0
	v_mov_b32_e32 v80, v0
	v_mov_b32_e32 v81, v0
	v_mov_b32_e32 v82, v0
	v_mov_b32_e32 v83, v0
	v_mov_b32_e32 v84, v0
	v_mov_b32_e32 v85, v0
	v_mov_b32_e32 v86, v0
	v_mov_b32_e32 v87, v0
	v_mov_b32_e32 v88, v0
	v_mov_b32_e32 v89, v0
	v_mov_b32_e32 v90, v0
	v_mov_b32_e32 v91, v0
	v_mov_b32_e32 v92, v0
	v_mov_b32_e32 v93, v0
	v_mov_b32_e32 v94, v0
	v_mov_b32_e32 v95, v0
	v_mov_b32_e32 v32, v0
	v_mov_b32_e32 v33, v0
	v_mov_b32_e32 v34, v0
	v_mov_b32_e32 v35, v0
	v_mov_b32_e32 v36, v0
	v_mov_b32_e32 v37, v0
	v_mov_b32_e32 v38, v0
	v_mov_b32_e32 v39, v0
	v_mov_b32_e32 v40, v0
	v_mov_b32_e32 v41, v0
	v_mov_b32_e32 v42, v0
	v_mov_b32_e32 v43, v0
	v_mov_b32_e32 v44, v0
	v_mov_b32_e32 v45, v0
	v_mov_b32_e32 v46, v0
	v_mov_b32_e32 v47, v0
	v_mov_b32_e32 v48, v0
	v_mov_b32_e32 v49, v0
	v_mov_b32_e32 v50, v0
	v_mov_b32_e32 v51, v0
	v_mov_b32_e32 v52, v0
	v_mov_b32_e32 v53, v0
	v_mov_b32_e32 v54, v0
	v_mov_b32_e32 v55, v0
	v_mov_b32_e32 v56, v0
	v_mov_b32_e32 v57, v0
	v_mov_b32_e32 v58, v0
	v_mov_b32_e32 v59, v0
	v_mov_b32_e32 v60, v0
	v_mov_b32_e32 v61, v0
	v_mov_b32_e32 v62, v0
	v_mov_b32_e32 v63, v0
	v_mov_b32_e32 v96, v0
	v_mov_b32_e32 v97, v0
	v_mov_b32_e32 v98, v0
	v_mov_b32_e32 v99, v0
	v_mov_b32_e32 v100, v0
	v_mov_b32_e32 v101, v0
	v_mov_b32_e32 v102, v0
	v_mov_b32_e32 v103, v0
	v_mov_b32_e32 v104, v0
	v_mov_b32_e32 v105, v0
	v_mov_b32_e32 v106, v0
	v_mov_b32_e32 v107, v0
	v_mov_b32_e32 v108, v0
	v_mov_b32_e32 v109, v0
	v_mov_b32_e32 v110, v0
	v_mov_b32_e32 v111, v0
	v_mov_b32_e32 v112, v0
	v_mov_b32_e32 v113, v0
	v_mov_b32_e32 v114, v0
	v_mov_b32_e32 v115, v0
	v_mov_b32_e32 v116, v0
	v_mov_b32_e32 v117, v0
	v_mov_b32_e32 v118, v0
	v_mov_b32_e32 v119, v0
	v_mov_b32_e32 v120, v0
	v_mov_b32_e32 v121, v0
	v_mov_b32_e32 v122, v0
	v_mov_b32_e32 v123, v0
	v_mov_b32_e32 v124, v0
	v_mov_b32_e32 v125, v0
	v_mov_b32_e32 v126, v0
	v_mov_b32_e32 v127, v0

; template <class Epi, class Sched, bool ALIGN_EPI = false, bool SP2 = false>
; __device__ __forceinline__ void gemm_phase(PG8_LAS unsigned char* lds, const Gemm g, const Sched& S, const Epi& E, int tid_in) {
;     ...
;         for (int t = 0; t < nt; t += 2) {
;             const bool last = (t == nt - 2);
;             const char* a1 = cA + (size_t)(t + 1) * kstep;
;             const char* a2 = last ? nA : cA + (size_t)(t + 2) * kstep; const char* b2 = last ? nB : cB + (size_t)(t + 2) * kstep;
;     ...
;         if (!Epi::DUAL || cur.sel == 1) {
; #pragma unroll
;         for (int a = 0; a < 2; ++a)
; #pragma unroll
;             for (int b = 0; b < 2; ++b)
; #pragma unroll
;                 for (int m = 0; m < 4; ++m)
; #pragma unroll
;                     for (int n = 0; n < 2; ++n) acc[a][b][m][n] = (f32x4){0.f, 0.f, 0.f, 0.f};
;         }
;         cur = nxt; cA = nA; cB = nB; ++ui;
.LBB0_574:
	v_mov_b64_e32 v[0:1], 0
	v_mov_b64_e32 v[2:3], 0
	v_mov_b64_e32 v[4:5], 0
	v_mov_b64_e32 v[6:7], 0
	v_mov_b64_e32 v[8:9], 0
	v_mov_b64_e32 v[10:11], 0
	v_mov_b64_e32 v[12:13], 0
	v_mov_b64_e32 v[14:15], 0
	v_mov_b64_e32 v[16:17], 0
	v_mov_b64_e32 v[18:19], 0
	v_mov_b64_e32 v[20:21], 0
	v_mov_b64_e32 v[22:23], 0
	v_mov_b64_e32 v[24:25], 0
	v_mov_b64_e32 v[26:27], 0
	v_mov_b64_e32 v[28:29], 0
	v_mov_b64_e32 v[30:31], 0
	v_mov_b64_e32 v[32:33], 0
	v_mov_b64_e32 v[34:35], 0
	v_mov_b64_e32 v[36:37], 0
	v_mov_b64_e32 v[38:39], 0
	v_mov_b64_e32 v[40:41], 0
	v_mov_b64_e32 v[42:43], 0
	v_mov_b64_e32 v[44:45], 0
	v_mov_b64_e32 v[46:47], 0
	v_mov_b64_e32 v[48:49], 0
	v_mov_b64_e32 v[50:51], 0
	v_mov_b64_e32 v[52:53], 0
	v_mov_b64_e32 v[54:55], 0
	v_mov_b64_e32 v[56:57], 0
	v_mov_b64_e32 v[58:59], 0
	v_mov_b64_e32 v[60:61], 0
	v_mov_b64_e32 v[62:63], 0
	v_mov_b64_e32 v[64:65], 0
	v_mov_b64_e32 v[66:67], 0
	v_mov_b64_e32 v[68:69], 0
	v_mov_b64_e32 v[70:71], 0
	v_mov_b64_e32 v[72:73], 0
	v_mov_b64_e32 v[74:75], 0
	v_mov_b64_e32 v[76:77], 0
	v_mov_b64_e32 v[78:79], 0
	v_mov_b64_e32 v[88:89], 0
	v_mov_b64_e32 v[90:91], 0
	v_mov_b64_e32 v[92:93], 0
	v_mov_b64_e32 v[94:95], 0
	v_mov_b64_e32 v[96:97], 0
	v_mov_b64_e32 v[98:99], 0
	v_mov_b64_e32 v[100:101], 0
	v_mov_b64_e32 v[102:103], 0
	v_mov_b64_e32 v[112:113], 0
	v_mov_b64_e32 v[114:115], 0
	v_mov_b64_e32 v[116:117], 0
	v_mov_b64_e32 v[118:119], 0
	v_mov_b64_e32 v[120:121], 0
	v_mov_b64_e32 v[122:123], 0
	v_mov_b64_e32 v[132:133], 0
	v_mov_b64_e32 v[134:135], 0
	v_mov_b64_e32 v[136:137], 0
	v_mov_b64_e32 v[138:139], 0
	v_mov_b64_e32 v[140:141], 0
	v_mov_b64_e32 v[142:143], 0
	v_mov_b64_e32 v[152:153], 0
	v_mov_b64_e32 v[154:155], 0
	v_mov_b64_e32 v[156:157], 0
	v_mov_b64_e32 v[158:159], 0
	s_andn2_b64 vcc, exec, s[28:29]
	s_cbranch_vccnz .LBB0_577
	s_add_u32 s33, s10, 0x100
	v_mov_b32_e32 v0, 0
	s_addc_u32 s38, s11, 0
	s_mov_b32 s10, 0
	v_mov_b32_e32 v1, v0
	v_mov_b32_e32 v2, v0
	v_mov_b32_e32 v3, v0
	v_mov_b32_e32 v4, v0
	v_mov_b32_e32 v5, v0
	v_mov_b32_e32 v6, v0
	v_mov_b32_e32 v7, v0
	v_mov_b32_e32 v16, v0
	v_mov_b32_e32 v17, v0
	v_mov_b32_e32 v18, v0
	v_mov_b32_e32 v19, v0
	v_mov_b32_e32 v20, v0
	v_mov_b32_e32 v21, v0
	v_mov_b32_e32 v22, v0
	v_mov_b32_e32 v23, v0
	v_mov_b32_e32 v32, v0
	v_mov_b32_e32 v33, v0
	v_mov_b32_e32 v34, v0
	v_mov_b32_e32 v35, v0
	v_mov_b32_e32 v36, v0
	v_mov_b32_e32 v37, v0
	v_mov_b32_e32 v38, v0
	v_mov_b32_e32 v39, v0
	v_mov_b32_e32 v48, v0
	v_mov_b32_e32 v49, v0
	v_mov_b32_e32 v50, v0
	v_mov_b32_e32 v51, v0
	v_mov_b32_e32 v52, v0
	v_mov_b32_e32 v53, v0
	v_mov_b32_e32 v54, v0
	v_mov_b32_e32 v55, v0
	v_mov_b32_e32 v8, v0
	v_mov_b32_e32 v9, v0
	v_mov_b32_e32 v10, v0
	v_mov_b32_e32 v11, v0
	v_mov_b32_e32 v12, v0
	v_mov_b32_e32 v13, v0
	v_mov_b32_e32 v14, v0
	v_mov_b32_e32 v15, v0
	v_mov_b32_e32 v24, v0
	v_mov_b32_e32 v25, v0
	v_mov_b32_e32 v26, v0
	v_mov_b32_e32 v27, v0
	v_mov_b32_e32 v28, v0
	v_mov_b32_e32 v29, v0
	v_mov_b32_e32 v30, v0
	v_mov_b32_e32 v31, v0
	v_mov_b32_e32 v40, v0
	v_mov_b32_e32 v41, v0
	v_mov_b32_e32 v42, v0
	v_mov_b32_e32 v43, v0
	v_mov_b32_e32 v44, v0
	v_mov_b32_e32 v45, v0
	v_mov_b32_e32 v46, v0
	v_mov_b32_e32 v47, v0
	v_mov_b32_e32 v56, v0
	v_mov_b32_e32 v57, v0
	v_mov_b32_e32 v58, v0
	v_mov_b32_e32 v59, v0
	v_mov_b32_e32 v60, v0
	v_mov_b32_e32 v61, v0
	v_mov_b32_e32 v62, v0
	v_mov_b32_e32 v63, v0
	v_mov_b32_e32 v64, v0
	v_mov_b32_e32 v65, v0
	v_mov_b32_e32 v66, v0
	v_mov_b32_e32 v67, v0
	v_mov_b32_e32 v68, v0
	v_mov_b32_e32 v69, v0
	v_mov_b32_e32 v70, v0
	v_mov_b32_e32 v71, v0
	v_mov_b32_e32 v88, v0
	v_mov_b32_e32 v89, v0
	v_mov_b32_e32 v90, v0
	v_mov_b32_e32 v91, v0
	v_mov_b32_e32 v92, v0
	v_mov_b32_e32 v93, v0
	v_mov_b32_e32 v94, v0
	v_mov_b32_e32 v95, v0
	v_mov_b32_e32 v112, v0
	v_mov_b32_e32 v113, v0
	v_mov_b32_e32 v114, v0
	v_mov_b32_e32 v115, v0
	v_mov_b32_e32 v116, v0
	v_mov_b32_e32 v117, v0
	v_mov_b32_e32 v118, v0
	v_mov_b32_e32 v119, v0
	v_mov_b32_e32 v136, v0
	v_mov_b32_e32 v137, v0
	v_mov_b32_e32 v138, v0
	v_mov_b32_e32 v139, v0
	v_mov_b32_e32 v140, v0
	v_mov_b32_e32 v141, v0
	v_mov_b32_e32 v142, v0
	v_mov_b32_e32 v143, v0
	v_mov_b32_e32 v72, v0
	v_mov_b32_e32 v73, v0
	v_mov_b32_e32 v74, v0
	v_mov_b32_e32 v75, v0
	v_mov_b32_e32 v76, v0
	v_mov_b32_e32 v77, v0
	v_mov_b32_e32 v78, v0
	v_mov_b32_e32 v79, v0
	v_mov_b32_e32 v96, v0
	v_mov_b32_e32 v97, v0
	v_mov_b32_e32 v98, v0
	v_mov_b32_e32 v99, v0
	v_mov_b32_e32 v100, v0
	v_mov_b32_e32 v101, v0
	v_mov_b32_e32 v102, v0
	v_mov_b32_e32 v103, v0
	v_mov_b32_e32 v120, v0
	v_mov_b32_e32 v121, v0
	v_mov_b32_e32 v122, v0
	v_mov_b32_e32 v123, v0
	v_mov_b32_e32 v132, v0
	v_mov_b32_e32 v133, v0
	v_mov_b32_e32 v134, v0
	v_mov_b32_e32 v135, v0
	v_mov_b32_e32 v152, v0
	v_mov_b32_e32 v153, v0
	v_mov_b32_e32 v154, v0
	v_mov_b32_e32 v155, v0
	v_mov_b32_e32 v156, v0
	v_mov_b32_e32 v157, v0
	v_mov_b32_e32 v158, v0
	v_mov_b32_e32 v159, v0

; template <class Epi, class Sched, bool ALIGN_EPI = false, bool SP2 = false>
; __device__ __forceinline__ void gemm_phase(PG8_LAS unsigned char* lds, const Gemm g, const Sched& S, const Epi& E, int tid_in) {
;     ...
;         for (int t = 0; t < nt; t += 2) {
;             const bool last = (t == nt - 2);
;             const char* a1 = cA + (size_t)(t + 1) * kstep;
;             const char* a2 = last ? nA : cA + (size_t)(t + 2) * kstep; const char* b2 = last ? nB : cB + (size_t)(t + 2) * kstep;
;     ...
;         if (!Epi::DUAL || cur.sel == 1) {
; #pragma unroll
;         for (int a = 0; a < 2; ++a)
; #pragma unroll
;             for (int b = 0; b < 2; ++b)
; #pragma unroll
;                 for (int m = 0; m < 4; ++m)
; #pragma unroll
;                     for (int n = 0; n < 2; ++n) acc[a][b][m][n] = (f32x4){0.f, 0.f, 0.f, 0.f};
;         }
;         cur = nxt; cA = nA; cB = nB; ++ui;
.LBB0_631:
	v_mov_b64_e32 v[0:1], 0
	v_mov_b64_e32 v[2:3], 0
	v_mov_b64_e32 v[4:5], 0
	v_mov_b64_e32 v[6:7], 0
	v_mov_b64_e32 v[8:9], 0
	v_mov_b64_e32 v[10:11], 0
	v_mov_b64_e32 v[12:13], 0
	v_mov_b64_e32 v[14:15], 0
	v_mov_b64_e32 v[16:17], 0
	v_mov_b64_e32 v[18:19], 0
	v_mov_b64_e32 v[20:21], 0
	v_mov_b64_e32 v[22:23], 0
	v_mov_b64_e32 v[24:25], 0
	v_mov_b64_e32 v[26:27], 0
	v_mov_b64_e32 v[28:29], 0
	v_mov_b64_e32 v[30:31], 0
	v_mov_b64_e32 v[32:33], 0
	v_mov_b64_e32 v[34:35], 0
	v_mov_b64_e32 v[36:37], 0
	v_mov_b64_e32 v[38:39], 0
	v_mov_b64_e32 v[40:41], 0
	v_mov_b64_e32 v[42:43], 0
	v_mov_b64_e32 v[44:45], 0
	v_mov_b64_e32 v[46:47], 0
	v_mov_b64_e32 v[48:49], 0
	v_mov_b64_e32 v[50:51], 0
	v_mov_b64_e32 v[52:53], 0
	v_mov_b64_e32 v[54:55], 0
	v_mov_b64_e32 v[56:57], 0
	v_mov_b64_e32 v[58:59], 0
	v_mov_b64_e32 v[60:61], 0
	v_mov_b64_e32 v[62:63], 0
	v_mov_b64_e32 v[64:65], 0
	v_mov_b64_e32 v[66:67], 0
	v_mov_b64_e32 v[68:69], 0
	v_mov_b64_e32 v[70:71], 0
	v_mov_b64_e32 v[72:73], 0
	v_mov_b64_e32 v[74:75], 0
	v_mov_b64_e32 v[76:77], 0
	v_mov_b64_e32 v[78:79], 0
	v_mov_b64_e32 v[80:81], 0
	v_mov_b64_e32 v[82:83], 0
	v_mov_b64_e32 v[84:85], 0
	v_mov_b64_e32 v[86:87], 0
	v_mov_b64_e32 v[88:89], 0
	v_mov_b64_e32 v[90:91], 0
	v_mov_b64_e32 v[92:93], 0
	v_mov_b64_e32 v[94:95], 0
	v_mov_b64_e32 v[96:97], 0
	v_mov_b64_e32 v[98:99], 0
	v_mov_b64_e32 v[100:101], 0
	v_mov_b64_e32 v[102:103], 0
	v_mov_b64_e32 v[104:105], 0
	v_mov_b64_e32 v[106:107], 0
	v_mov_b64_e32 v[108:109], 0
	v_mov_b64_e32 v[110:111], 0
	v_mov_b64_e32 v[112:113], 0
	v_mov_b64_e32 v[114:115], 0
	v_mov_b64_e32 v[116:117], 0
	v_mov_b64_e32 v[118:119], 0
	v_mov_b64_e32 v[120:121], 0
	v_mov_b64_e32 v[122:123], 0
	v_mov_b64_e32 v[124:125], 0
	v_mov_b64_e32 v[126:127], 0
	s_andn2_b64 vcc, exec, s[26:27]
	s_cbranch_vccnz .LBB0_634
	s_add_u32 s58, s36, 0x100
	v_mov_b32_e32 v0, 0
	s_addc_u32 s59, s37, 0
	s_mov_b32 s38, 0
	v_mov_b32_e32 v1, v0
	v_mov_b32_e32 v2, v0
	v_mov_b32_e32 v3, v0
	v_mov_b32_e32 v4, v0
	v_mov_b32_e32 v5, v0
	v_mov_b32_e32 v6, v0
	v_mov_b32_e32 v7, v0
	v_mov_b32_e32 v16, v0
	v_mov_b32_e32 v17, v0
	v_mov_b32_e32 v18, v0
	v_mov_b32_e32 v19, v0
	v_mov_b32_e32 v20, v0
	v_mov_b32_e32 v21, v0
	v_mov_b32_e32 v22, v0
	v_mov_b32_e32 v23, v0
	v_mov_b32_e32 v32, v0
	v_mov_b32_e32 v33, v0
	v_mov_b32_e32 v34, v0
	v_mov_b32_e32 v35, v0
	v_mov_b32_e32 v36, v0
	v_mov_b32_e32 v37, v0
	v_mov_b32_e32 v38, v0
	v_mov_b32_e32 v39, v0
	v_mov_b32_e32 v48, v0
	v_mov_b32_e32 v49, v0
	v_mov_b32_e32 v50, v0
	v_mov_b32_e32 v51, v0
	v_mov_b32_e32 v52, v0
	v_mov_b32_e32 v53, v0
	v_mov_b32_e32 v54, v0
	v_mov_b32_e32 v55, v0
	v_mov_b32_e32 v8, v0
	v_mov_b32_e32 v9, v0
	v_mov_b32_e32 v10, v0
	v_mov_b32_e32 v11, v0
	v_mov_b32_e32 v12, v0
	v_mov_b32_e32 v13, v0
	v_mov_b32_e32 v14, v0
	v_mov_b32_e32 v15, v0
	v_mov_b32_e32 v24, v0
	v_mov_b32_e32 v25, v0
	v_mov_b32_e32 v26, v0
	v_mov_b32_e32 v27, v0
	v_mov_b32_e32 v28, v0
	v_mov_b32_e32 v29, v0
	v_mov_b32_e32 v30, v0
	v_mov_b32_e32 v31, v0
	v_mov_b32_e32 v40, v0
	v_mov_b32_e32 v41, v0
	v_mov_b32_e32 v42, v0
	v_mov_b32_e32 v43, v0
	v_mov_b32_e32 v44, v0
	v_mov_b32_e32 v45, v0
	v_mov_b32_e32 v46, v0
	v_mov_b32_e32 v47, v0
	v_mov_b32_e32 v56, v0
	v_mov_b32_e32 v57, v0
	v_mov_b32_e32 v58, v0
	v_mov_b32_e32 v59, v0
	v_mov_b32_e32 v60, v0
	v_mov_b32_e32 v61, v0
	v_mov_b32_e32 v62, v0
	v_mov_b32_e32 v63, v0
	v_mov_b32_e32 v64, v0
	v_mov_b32_e32 v65, v0
	v_mov_b32_e32 v66, v0
	v_mov_b32_e32 v67, v0
	v_mov_b32_e32 v68, v0
	v_mov_b32_e32 v69, v0
	v_mov_b32_e32 v70, v0
	v_mov_b32_e32 v71, v0
	v_mov_b32_e32 v80, v0
	v_mov_b32_e32 v81, v0
	v_mov_b32_e32 v82, v0
	v_mov_b32_e32 v83, v0
	v_mov_b32_e32 v84, v0
	v_mov_b32_e32 v85, v0
	v_mov_b32_e32 v86, v0
	v_mov_b32_e32 v87, v0
	v_mov_b32_e32 v96, v0
	v_mov_b32_e32 v97, v0
	v_mov_b32_e32 v98, v0
	v_mov_b32_e32 v99, v0
	v_mov_b32_e32 v100, v0
	v_mov_b32_e32 v101, v0
	v_mov_b32_e32 v102, v0
	v_mov_b32_e32 v103, v0
	v_mov_b32_e32 v112, v0
	v_mov_b32_e32 v113, v0
	v_mov_b32_e32 v114, v0
	v_mov_b32_e32 v115, v0
	v_mov_b32_e32 v116, v0
	v_mov_b32_e32 v117, v0
	v_mov_b32_e32 v118, v0
	v_mov_b32_e32 v119, v0
	v_mov_b32_e32 v72, v0
	v_mov_b32_e32 v73, v0
	v_mov_b32_e32 v74, v0
	v_mov_b32_e32 v75, v0
	v_mov_b32_e32 v76, v0
	v_mov_b32_e32 v77, v0
	v_mov_b32_e32 v78, v0
	v_mov_b32_e32 v79, v0
	v_mov_b32_e32 v88, v0
	v_mov_b32_e32 v89, v0
	v_mov_b32_e32 v90, v0
	v_mov_b32_e32 v91, v0
	v_mov_b32_e32 v92, v0
	v_mov_b32_e32 v93, v0
	v_mov_b32_e32 v94, v0
	v_mov_b32_e32 v95, v0
	v_mov_b32_e32 v104, v0
	v_mov_b32_e32 v105, v0
	v_mov_b32_e32 v106, v0
	v_mov_b32_e32 v107, v0
	v_mov_b32_e32 v108, v0
	v_mov_b32_e32 v109, v0
	v_mov_b32_e32 v110, v0
	v_mov_b32_e32 v111, v0
	v_mov_b32_e32 v124, v0
	v_mov_b32_e32 v125, v0
	v_mov_b32_e32 v126, v0
	v_mov_b32_e32 v127, v0
	v_mov_b32_e32 v120, v0
	v_mov_b32_e32 v121, v0
	v_mov_b32_e32 v122, v0
	v_mov_b32_e32 v123, v0

; template <class Epi, class Sched, bool ALIGN_EPI = false, bool SP2 = false>
; __device__ __forceinline__ void gemm_phase(PG8_LAS unsigned char* lds, const Gemm g, const Sched& S, const Epi& E, int tid_in) {
;     ...
;         for (int t = 0; t < nt; t += 2) {
;             const bool last = (t == nt - 2);
;             const char* a1 = cA + (size_t)(t + 1) * kstep;
;             const char* a2 = last ? nA : cA + (size_t)(t + 2) * kstep; const char* b2 = last ? nB : cB + (size_t)(t + 2) * kstep;
;     ...
;         if (!Epi::DUAL || cur.sel == 1) {
; #pragma unroll
;         for (int a = 0; a < 2; ++a)
; #pragma unroll
;             for (int b = 0; b < 2; ++b)
; #pragma unroll
;                 for (int m = 0; m < 4; ++m)
; #pragma unroll
;                     for (int n = 0; n < 2; ++n) acc[a][b][m][n] = (f32x4){0.f, 0.f, 0.f, 0.f};
;         }
;         cur = nxt; cA = nA; cB = nB; ++ui;
.LBB0_652:
	v_mov_b64_e32 v[0:1], 0
	v_mov_b64_e32 v[2:3], 0
	v_mov_b64_e32 v[4:5], 0
	v_mov_b64_e32 v[6:7], 0
	v_mov_b64_e32 v[8:9], 0
	v_mov_b64_e32 v[10:11], 0
	v_mov_b64_e32 v[12:13], 0
	v_mov_b64_e32 v[14:15], 0
	v_mov_b64_e32 v[16:17], 0
	v_mov_b64_e32 v[18:19], 0
	v_mov_b64_e32 v[20:21], 0
	v_mov_b64_e32 v[22:23], 0
	v_mov_b64_e32 v[24:25], 0
	v_mov_b64_e32 v[26:27], 0
	v_mov_b64_e32 v[28:29], 0
	v_mov_b64_e32 v[30:31], 0
	v_mov_b64_e32 v[32:33], 0
	v_mov_b64_e32 v[34:35], 0
	v_mov_b64_e32 v[36:37], 0
	v_mov_b64_e32 v[38:39], 0
	v_mov_b64_e32 v[40:41], 0
	v_mov_b64_e32 v[42:43], 0
	v_mov_b64_e32 v[44:45], 0
	v_mov_b64_e32 v[46:47], 0
	v_mov_b64_e32 v[48:49], 0
	v_mov_b64_e32 v[50:51], 0
	v_mov_b64_e32 v[52:53], 0
	v_mov_b64_e32 v[54:55], 0
	v_mov_b64_e32 v[56:57], 0
	v_mov_b64_e32 v[58:59], 0
	v_mov_b64_e32 v[60:61], 0
	v_mov_b64_e32 v[62:63], 0
	v_mov_b64_e32 v[64:65], 0
	v_mov_b64_e32 v[66:67], 0
	v_mov_b64_e32 v[68:69], 0
	v_mov_b64_e32 v[70:71], 0
	v_mov_b64_e32 v[72:73], 0
	v_mov_b64_e32 v[74:75], 0
	v_mov_b64_e32 v[76:77], 0
	v_mov_b64_e32 v[78:79], 0
	v_mov_b64_e32 v[80:81], 0
	v_mov_b64_e32 v[82:83], 0
	v_mov_b64_e32 v[84:85], 0
	v_mov_b64_e32 v[86:87], 0
	v_mov_b64_e32 v[88:89], 0
	v_mov_b64_e32 v[90:91], 0
	v_mov_b64_e32 v[92:93], 0
	v_mov_b64_e32 v[94:95], 0
	v_mov_b64_e32 v[96:97], 0
	v_mov_b64_e32 v[98:99], 0
	v_mov_b64_e32 v[100:101], 0
	v_mov_b64_e32 v[102:103], 0
	v_mov_b64_e32 v[104:105], 0
	v_mov_b64_e32 v[106:107], 0
	v_mov_b64_e32 v[108:109], 0
	v_mov_b64_e32 v[110:111], 0
	v_mov_b64_e32 v[112:113], 0
	v_mov_b64_e32 v[114:115], 0
	v_mov_b64_e32 v[116:117], 0
	v_mov_b64_e32 v[118:119], 0
	v_mov_b64_e32 v[120:121], 0
	v_mov_b64_e32 v[122:123], 0
	v_mov_b64_e32 v[124:125], 0
	v_mov_b64_e32 v[126:127], 0
	s_andn2_b64 vcc, exec, s[16:17]
	s_cbranch_vccnz .LBB0_655
	s_add_u32 s26, s26, 0x80
	s_addc_u32 s27, s27, 0
	s_add_u32 s54, s28, 0x100
	v_mov_b32_e32 v0, 0
	s_addc_u32 s55, s29, 0
	s_mov_b32 s28, 0
	v_mov_b32_e32 v1, v0
	v_mov_b32_e32 v2, v0
	v_mov_b32_e32 v3, v0
	v_mov_b32_e32 v4, v0
	v_mov_b32_e32 v5, v0
	v_mov_b32_e32 v6, v0
	v_mov_b32_e32 v7, v0
	v_mov_b32_e32 v8, v0
	v_mov_b32_e32 v9, v0
	v_mov_b32_e32 v10, v0
	v_mov_b32_e32 v11, v0
	v_mov_b32_e32 v12, v0
	v_mov_b32_e32 v13, v0
	v_mov_b32_e32 v14, v0
	v_mov_b32_e32 v15, v0
	v_mov_b32_e32 v16, v0
	v_mov_b32_e32 v17, v0
	v_mov_b32_e32 v18, v0
	v_mov_b32_e32 v19, v0
	v_mov_b32_e32 v20, v0
	v_mov_b32_e32 v21, v0
	v_mov_b32_e32 v22, v0
	v_mov_b32_e32 v23, v0
	v_mov_b32_e32 v24, v0
	v_mov_b32_e32 v25, v0
	v_mov_b32_e32 v26, v0
	v_mov_b32_e32 v27, v0
	v_mov_b32_e32 v28, v0
	v_mov_b32_e32 v29, v0
	v_mov_b32_e32 v30, v0
	v_mov_b32_e32 v31, v0
	v_mov_b32_e32 v64, v0
	v_mov_b32_e32 v65, v0
	v_mov_b32_e32 v66, v0
	v_mov_b32_e32 v67, v0
	v_mov_b32_e32 v68, v0
	v_mov_b32_e32 v69, v0
	v_mov_b32_e32 v70, v0
	v_mov_b32_e32 v71, v0
	v_mov_b32_e32 v72, v0
	v_mov_b32_e32 v73, v0
	v_mov_b32_e32 v74, v0
	v_mov_b32_e32 v75, v0
	v_mov_b32_e32 v76, v0
	v_mov_b32_e32 v77, v0
	v_mov_b32_e32 v78, v0
	v_mov_b32_e32 v79, v0
	v_mov_b32_e32 v80, v0
	v_mov_b32_e32 v81, v0
	v_mov_b32_e32 v82, v0
	v_mov_b32_e32 v83, v0
	v_mov_b32_e32 v84, v0
	v_mov_b32_e32 v85, v0
	v_mov_b32_e32 v86, v0
	v_mov_b32_e32 v87, v0
	v_mov_b32_e32 v88, v0
	v_mov_b32_e32 v89, v0
	v_mov_b32_e32 v90, v0
	v_mov_b32_e32 v91, v0
	v_mov_b32_e32 v92, v0
	v_mov_b32_e32 v93, v0
	v_mov_b32_e32 v94, v0
	v_mov_b32_e32 v95, v0
	v_mov_b32_e32 v32, v0
	v_mov_b32_e32 v33, v0
	v_mov_b32_e32 v34, v0
	v_mov_b32_e32 v35, v0
	v_mov_b32_e32 v36, v0
	v_mov_b32_e32 v37, v0
	v_mov_b32_e32 v38, v0
	v_mov_b32_e32 v39, v0
	v_mov_b32_e32 v40, v0
	v_mov_b32_e32 v41, v0
	v_mov_b32_e32 v42, v0
	v_mov_b32_e32 v43, v0
	v_mov_b32_e32 v44, v0
	v_mov_b32_e32 v45, v0
	v_mov_b32_e32 v46, v0
	v_mov_b32_e32 v47, v0
	v_mov_b32_e32 v48, v0
	v_mov_b32_e32 v49, v0
	v_mov_b32_e32 v50, v0
	v_mov_b32_e32 v51, v0
	v_mov_b32_e32 v52, v0
	v_mov_b32_e32 v53, v0
	v_mov_b32_e32 v54, v0
	v_mov_b32_e32 v55, v0
	v_mov_b32_e32 v56, v0
	v_mov_b32_e32 v57, v0
	v_mov_b32_e32 v58, v0
	v_mov_b32_e32 v59, v0
	v_mov_b32_e32 v60, v0
	v_mov_b32_e32 v61, v0
	v_mov_b32_e32 v62, v0
	v_mov_b32_e32 v63, v0
	v_mov_b32_e32 v96, v0
	v_mov_b32_e32 v97, v0
	v_mov_b32_e32 v98, v0
	v_mov_b32_e32 v99, v0
	v_mov_b32_e32 v100, v0
	v_mov_b32_e32 v101, v0
	v_mov_b32_e32 v102, v0
	v_mov_b32_e32 v103, v0
	v_mov_b32_e32 v104, v0
	v_mov_b32_e32 v105, v0
	v_mov_b32_e32 v106, v0
	v_mov_b32_e32 v107, v0
	v_mov_b32_e32 v108, v0
	v_mov_b32_e32 v109, v0
	v_mov_b32_e32 v110, v0
	v_mov_b32_e32 v111, v0
	v_mov_b32_e32 v112, v0
	v_mov_b32_e32 v113, v0
	v_mov_b32_e32 v114, v0
	v_mov_b32_e32 v115, v0
	v_mov_b32_e32 v116, v0
	v_mov_b32_e32 v117, v0
	v_mov_b32_e32 v118, v0
	v_mov_b32_e32 v119, v0
	v_mov_b32_e32 v124, v0
	v_mov_b32_e32 v125, v0
	v_mov_b32_e32 v126, v0
	v_mov_b32_e32 v127, v0
	v_mov_b32_e32 v120, v0
	v_mov_b32_e32 v121, v0
	v_mov_b32_e32 v122, v0
	v_mov_b32_e32 v123, v0

; template <class Epi, class Sched, bool ALIGN_EPI = false, bool SP2 = false>
; __device__ __forceinline__ void gemm_phase(PG8_LAS unsigned char* lds, const Gemm g, const Sched& S, const Epi& E, int tid_in) {
;     ...
;         for (int t = 0; t < nt; t += 2) {
;             const bool last = (t == nt - 2);
;             const char* a1 = cA + (size_t)(t + 1) * kstep;
;             const char* a2 = last ? nA : cA + (size_t)(t + 2) * kstep; const char* b2 = last ? nB : cB + (size_t)(t + 2) * kstep;
;     ...
;         if (!Epi::DUAL || cur.sel == 1) {
; #pragma unroll
;         for (int a = 0; a < 2; ++a)
; #pragma unroll
;             for (int b = 0; b < 2; ++b)
; #pragma unroll
;                 for (int m = 0; m < 4; ++m)
; #pragma unroll
;                     for (int n = 0; n < 2; ++n) acc[a][b][m][n] = (f32x4){0.f, 0.f, 0.f, 0.f};
;         }
;         cur = nxt; cA = nA; cB = nB; ++ui;
.LBB0_1170:
	v_mov_b64_e32 v[0:1], 0
	v_mov_b64_e32 v[2:3], 0
	v_mov_b64_e32 v[4:5], 0
	v_mov_b64_e32 v[6:7], 0
	v_mov_b64_e32 v[8:9], 0
	v_mov_b64_e32 v[10:11], 0
	v_mov_b64_e32 v[12:13], 0
	v_mov_b64_e32 v[14:15], 0
	v_mov_b64_e32 v[16:17], 0
	v_mov_b64_e32 v[18:19], 0
	v_mov_b64_e32 v[20:21], 0
	v_mov_b64_e32 v[22:23], 0
	v_mov_b64_e32 v[24:25], 0
	v_mov_b64_e32 v[26:27], 0
	v_mov_b64_e32 v[28:29], 0
	v_mov_b64_e32 v[30:31], 0
	v_mov_b64_e32 v[32:33], 0
	v_mov_b64_e32 v[34:35], 0
	v_mov_b64_e32 v[36:37], 0
	v_mov_b64_e32 v[38:39], 0
	v_mov_b64_e32 v[40:41], 0
	v_mov_b64_e32 v[42:43], 0
	v_mov_b64_e32 v[44:45], 0
	v_mov_b64_e32 v[46:47], 0
	v_mov_b64_e32 v[48:49], 0
	v_mov_b64_e32 v[50:51], 0
	v_mov_b64_e32 v[52:53], 0
	v_mov_b64_e32 v[54:55], 0
	v_mov_b64_e32 v[56:57], 0
	v_mov_b64_e32 v[58:59], 0
	v_mov_b64_e32 v[60:61], 0
	v_mov_b64_e32 v[62:63], 0
	v_mov_b64_e32 v[64:65], 0
	v_mov_b64_e32 v[66:67], 0
	v_mov_b64_e32 v[68:69], 0
	v_mov_b64_e32 v[70:71], 0
	v_mov_b64_e32 v[72:73], 0
	v_mov_b64_e32 v[74:75], 0
	v_mov_b64_e32 v[76:77], 0
	v_mov_b64_e32 v[78:79], 0
	v_mov_b64_e32 v[80:81], 0
	v_mov_b64_e32 v[82:83], 0
	v_mov_b64_e32 v[84:85], 0
	v_mov_b64_e32 v[86:87], 0
	v_mov_b64_e32 v[88:89], 0
	v_mov_b64_e32 v[90:91], 0
	v_mov_b64_e32 v[92:93], 0
	v_mov_b64_e32 v[94:95], 0
	v_mov_b64_e32 v[96:97], 0
	v_mov_b64_e32 v[98:99], 0
	v_mov_b64_e32 v[100:101], 0
	v_mov_b64_e32 v[102:103], 0
	v_mov_b64_e32 v[104:105], 0
	v_mov_b64_e32 v[106:107], 0
	v_mov_b64_e32 v[108:109], 0
	v_mov_b64_e32 v[110:111], 0
	v_mov_b64_e32 v[112:113], 0
	v_mov_b64_e32 v[114:115], 0
	v_mov_b64_e32 v[116:117], 0
	v_mov_b64_e32 v[118:119], 0
	v_mov_b64_e32 v[120:121], 0
	v_mov_b64_e32 v[122:123], 0
	v_mov_b64_e32 v[124:125], 0
	v_mov_b64_e32 v[126:127], 0
	s_andn2_b64 vcc, exec, s[24:25]
	s_cbranch_vccnz .LBB0_1173
	s_add_u32 s30, s30, 0x80
	s_addc_u32 s31, s31, 0
	s_add_u32 s57, s34, 0x100
	v_mov_b32_e32 v0, 0
	s_addc_u32 s58, s35, 0
	s_mov_b32 s34, 0
	v_mov_b32_e32 v1, v0
	v_mov_b32_e32 v2, v0
	v_mov_b32_e32 v3, v0
	v_mov_b32_e32 v4, v0
	v_mov_b32_e32 v5, v0
	v_mov_b32_e32 v6, v0
	v_mov_b32_e32 v7, v0
	v_mov_b32_e32 v16, v0
	v_mov_b32_e32 v17, v0
	v_mov_b32_e32 v18, v0
	v_mov_b32_e32 v19, v0
	v_mov_b32_e32 v20, v0
	v_mov_b32_e32 v21, v0
	v_mov_b32_e32 v22, v0
	v_mov_b32_e32 v23, v0
	v_mov_b32_e32 v32, v0
	v_mov_b32_e32 v33, v0
	v_mov_b32_e32 v34, v0
	v_mov_b32_e32 v35, v0
	v_mov_b32_e32 v36, v0
	v_mov_b32_e32 v37, v0
	v_mov_b32_e32 v38, v0
	v_mov_b32_e32 v39, v0
	v_mov_b32_e32 v48, v0
	v_mov_b32_e32 v49, v0
	v_mov_b32_e32 v50, v0
	v_mov_b32_e32 v51, v0
	v_mov_b32_e32 v52, v0
	v_mov_b32_e32 v53, v0
	v_mov_b32_e32 v54, v0
	v_mov_b32_e32 v55, v0
	v_mov_b32_e32 v8, v0
	v_mov_b32_e32 v9, v0
	v_mov_b32_e32 v10, v0
	v_mov_b32_e32 v11, v0
	v_mov_b32_e32 v12, v0
	v_mov_b32_e32 v13, v0
	v_mov_b32_e32 v14, v0
	v_mov_b32_e32 v15, v0
	v_mov_b32_e32 v24, v0
	v_mov_b32_e32 v25, v0
	v_mov_b32_e32 v26, v0
	v_mov_b32_e32 v27, v0
	v_mov_b32_e32 v28, v0
	v_mov_b32_e32 v29, v0
	v_mov_b32_e32 v30, v0
	v_mov_b32_e32 v31, v0
	v_mov_b32_e32 v40, v0
	v_mov_b32_e32 v41, v0
	v_mov_b32_e32 v42, v0
	v_mov_b32_e32 v43, v0
	v_mov_b32_e32 v44, v0
	v_mov_b32_e32 v45, v0
	v_mov_b32_e32 v46, v0
	v_mov_b32_e32 v47, v0
	v_mov_b32_e32 v56, v0
	v_mov_b32_e32 v57, v0
	v_mov_b32_e32 v58, v0
	v_mov_b32_e32 v59, v0
	v_mov_b32_e32 v60, v0
	v_mov_b32_e32 v61, v0
	v_mov_b32_e32 v62, v0
	v_mov_b32_e32 v63, v0
	v_mov_b32_e32 v64, v0
	v_mov_b32_e32 v65, v0
	v_mov_b32_e32 v66, v0
	v_mov_b32_e32 v67, v0
	v_mov_b32_e32 v68, v0
	v_mov_b32_e32 v69, v0
	v_mov_b32_e32 v70, v0
	v_mov_b32_e32 v71, v0
	v_mov_b32_e32 v80, v0
	v_mov_b32_e32 v81, v0
	v_mov_b32_e32 v82, v0
	v_mov_b32_e32 v83, v0
	v_mov_b32_e32 v84, v0
	v_mov_b32_e32 v85, v0
	v_mov_b32_e32 v86, v0
	v_mov_b32_e32 v87, v0
	v_mov_b32_e32 v96, v0
	v_mov_b32_e32 v97, v0
	v_mov_b32_e32 v98, v0
	v_mov_b32_e32 v99, v0
	v_mov_b32_e32 v100, v0
	v_mov_b32_e32 v101, v0
	v_mov_b32_e32 v102, v0
	v_mov_b32_e32 v103, v0
	v_mov_b32_e32 v112, v0
	v_mov_b32_e32 v113, v0
	v_mov_b32_e32 v114, v0
	v_mov_b32_e32 v115, v0
	v_mov_b32_e32 v116, v0
	v_mov_b32_e32 v117, v0
	v_mov_b32_e32 v118, v0
	v_mov_b32_e32 v119, v0
	v_mov_b32_e32 v72, v0
	v_mov_b32_e32 v73, v0
	v_mov_b32_e32 v74, v0
	v_mov_b32_e32 v75, v0
	v_mov_b32_e32 v76, v0
	v_mov_b32_e32 v77, v0
	v_mov_b32_e32 v78, v0
	v_mov_b32_e32 v79, v0
	v_mov_b32_e32 v88, v0
	v_mov_b32_e32 v89, v0
	v_mov_b32_e32 v90, v0
	v_mov_b32_e32 v91, v0
	v_mov_b32_e32 v92, v0
	v_mov_b32_e32 v93, v0
	v_mov_b32_e32 v94, v0
	v_mov_b32_e32 v95, v0
	v_mov_b32_e32 v104, v0
	v_mov_b32_e32 v105, v0
	v_mov_b32_e32 v106, v0
	v_mov_b32_e32 v107, v0
	v_mov_b32_e32 v108, v0
	v_mov_b32_e32 v109, v0
	v_mov_b32_e32 v110, v0
	v_mov_b32_e32 v111, v0
	v_mov_b32_e32 v120, v0
	v_mov_b32_e32 v121, v0
	v_mov_b32_e32 v122, v0
	v_mov_b32_e32 v123, v0
	v_mov_b32_e32 v124, v0
	v_mov_b32_e32 v125, v0
	v_mov_b32_e32 v126, v0
	v_mov_b32_e32 v127, v0

; template <class Epi, class Sched, bool ALIGN_EPI = false, bool SP2 = false>
; __device__ __forceinline__ void gemm_phase(PG8_LAS unsigned char* lds, const Gemm g, const Sched& S, const Epi& E, int tid_in) {
;     ...
;         for (int t = 0; t < nt; t += 2) {
;             const bool last = (t == nt - 2);
;             const char* a1 = cA + (size_t)(t + 1) * kstep;
;             const char* a2 = last ? nA : cA + (size_t)(t + 2) * kstep; const char* b2 = last ? nB : cB + (size_t)(t + 2) * kstep;
;     ...
;         if (!Epi::DUAL || cur.sel == 1) {
; #pragma unroll
;         for (int a = 0; a < 2; ++a)
; #pragma unroll
;             for (int b = 0; b < 2; ++b)
; #pragma unroll
;                 for (int m = 0; m < 4; ++m)
; #pragma unroll
;                     for (int n = 0; n < 2; ++n) acc[a][b][m][n] = (f32x4){0.f, 0.f, 0.f, 0.f};
;         }
;         cur = nxt; cA = nA; cB = nB; ++ui;
.LBB0_1279:
	v_mov_b64_e32 v[0:1], 0
	v_mov_b64_e32 v[2:3], 0
	v_mov_b64_e32 v[4:5], 0
	v_mov_b64_e32 v[6:7], 0
	v_mov_b64_e32 v[8:9], 0
	v_mov_b64_e32 v[10:11], 0
	v_mov_b64_e32 v[12:13], 0
	v_mov_b64_e32 v[14:15], 0
	v_mov_b64_e32 v[16:17], 0
	v_mov_b64_e32 v[18:19], 0
	v_mov_b64_e32 v[20:21], 0
	v_mov_b64_e32 v[22:23], 0
	v_mov_b64_e32 v[24:25], 0
	v_mov_b64_e32 v[26:27], 0
	v_mov_b64_e32 v[28:29], 0
	v_mov_b64_e32 v[30:31], 0
	v_mov_b64_e32 v[32:33], 0
	v_mov_b64_e32 v[34:35], 0
	v_mov_b64_e32 v[36:37], 0
	v_mov_b64_e32 v[38:39], 0
	v_mov_b64_e32 v[40:41], 0
	v_mov_b64_e32 v[42:43], 0
	v_mov_b64_e32 v[44:45], 0
	v_mov_b64_e32 v[46:47], 0
	v_mov_b64_e32 v[48:49], 0
	v_mov_b64_e32 v[50:51], 0
	v_mov_b64_e32 v[52:53], 0
	v_mov_b64_e32 v[54:55], 0
	v_mov_b64_e32 v[56:57], 0
	v_mov_b64_e32 v[58:59], 0
	v_mov_b64_e32 v[60:61], 0
	v_mov_b64_e32 v[62:63], 0
	v_mov_b64_e32 v[64:65], 0
	v_mov_b64_e32 v[66:67], 0
	v_mov_b64_e32 v[68:69], 0
	v_mov_b64_e32 v[70:71], 0
	v_mov_b64_e32 v[72:73], 0
	v_mov_b64_e32 v[74:75], 0
	v_mov_b64_e32 v[76:77], 0
	v_mov_b64_e32 v[78:79], 0
	v_mov_b64_e32 v[80:81], 0
	v_mov_b64_e32 v[82:83], 0
	v_mov_b64_e32 v[84:85], 0
	v_mov_b64_e32 v[86:87], 0
	v_mov_b64_e32 v[88:89], 0
	v_mov_b64_e32 v[90:91], 0
	v_mov_b64_e32 v[92:93], 0
	v_mov_b64_e32 v[94:95], 0
	v_mov_b64_e32 v[96:97], 0
	v_mov_b64_e32 v[98:99], 0
	v_mov_b64_e32 v[100:101], 0
	v_mov_b64_e32 v[102:103], 0
	v_mov_b64_e32 v[104:105], 0
	v_mov_b64_e32 v[106:107], 0
	v_mov_b64_e32 v[108:109], 0
	v_mov_b64_e32 v[110:111], 0
	v_mov_b64_e32 v[112:113], 0
	v_mov_b64_e32 v[114:115], 0
	v_mov_b64_e32 v[116:117], 0
	v_mov_b64_e32 v[118:119], 0
	v_mov_b64_e32 v[120:121], 0
	v_mov_b64_e32 v[122:123], 0
	v_mov_b64_e32 v[124:125], 0
	v_mov_b64_e32 v[126:127], 0
	s_andn2_b64 vcc, exec, s[22:23]
	s_cbranch_vccnz .LBB0_1282
	s_add_u32 s28, s28, 0x80
	s_addc_u32 s29, s29, 0
	s_add_u32 s54, s30, 0x100
	v_mov_b32_e32 v0, 0
	s_addc_u32 s55, s31, 0
	s_mov_b32 s30, 0
	v_mov_b32_e32 v1, v0
	v_mov_b32_e32 v2, v0
	v_mov_b32_e32 v3, v0
	v_mov_b32_e32 v4, v0
	v_mov_b32_e32 v5, v0
	v_mov_b32_e32 v6, v0
	v_mov_b32_e32 v7, v0
	v_mov_b32_e32 v20, v0
	v_mov_b32_e32 v21, v0
	v_mov_b32_e32 v22, v0
	v_mov_b32_e32 v23, v0
	v_mov_b32_e32 v16, v0
	v_mov_b32_e32 v17, v0
	v_mov_b32_e32 v18, v0
	v_mov_b32_e32 v19, v0
	v_mov_b32_e32 v36, v0
	v_mov_b32_e32 v37, v0
	v_mov_b32_e32 v38, v0
	v_mov_b32_e32 v39, v0
	v_mov_b32_e32 v32, v0
	v_mov_b32_e32 v33, v0
	v_mov_b32_e32 v34, v0
	v_mov_b32_e32 v35, v0
	v_mov_b32_e32 v52, v0
	v_mov_b32_e32 v53, v0
	v_mov_b32_e32 v54, v0
	v_mov_b32_e32 v55, v0
	v_mov_b32_e32 v48, v0
	v_mov_b32_e32 v49, v0
	v_mov_b32_e32 v50, v0
	v_mov_b32_e32 v51, v0
	v_mov_b32_e32 v12, v0
	v_mov_b32_e32 v13, v0
	v_mov_b32_e32 v14, v0
	v_mov_b32_e32 v15, v0
	v_mov_b32_e32 v8, v0
	v_mov_b32_e32 v9, v0
	v_mov_b32_e32 v10, v0
	v_mov_b32_e32 v11, v0
	v_mov_b32_e32 v28, v0
	v_mov_b32_e32 v29, v0
	v_mov_b32_e32 v30, v0
	v_mov_b32_e32 v31, v0
	v_mov_b32_e32 v24, v0
	v_mov_b32_e32 v25, v0
	v_mov_b32_e32 v26, v0
	v_mov_b32_e32 v27, v0
	v_mov_b32_e32 v44, v0
	v_mov_b32_e32 v45, v0
	v_mov_b32_e32 v46, v0
	v_mov_b32_e32 v47, v0
	v_mov_b32_e32 v40, v0
	v_mov_b32_e32 v41, v0
	v_mov_b32_e32 v42, v0
	v_mov_b32_e32 v43, v0
	v_mov_b32_e32 v60, v0
	v_mov_b32_e32 v61, v0
	v_mov_b32_e32 v62, v0
	v_mov_b32_e32 v63, v0
	v_mov_b32_e32 v56, v0
	v_mov_b32_e32 v57, v0
	v_mov_b32_e32 v58, v0
	v_mov_b32_e32 v59, v0
	v_mov_b32_e32 v68, v0
	v_mov_b32_e32 v69, v0
	v_mov_b32_e32 v70, v0
	v_mov_b32_e32 v71, v0
	v_mov_b32_e32 v64, v0
	v_mov_b32_e32 v65, v0
	v_mov_b32_e32 v66, v0
	v_mov_b32_e32 v67, v0
	v_mov_b32_e32 v84, v0
	v_mov_b32_e32 v85, v0
	v_mov_b32_e32 v86, v0
	v_mov_b32_e32 v87, v0
	v_mov_b32_e32 v80, v0
	v_mov_b32_e32 v81, v0
	v_mov_b32_e32 v82, v0
	v_mov_b32_e32 v83, v0
	v_mov_b32_e32 v100, v0
	v_mov_b32_e32 v101, v0
	v_mov_b32_e32 v102, v0
	v_mov_b32_e32 v103, v0
	v_mov_b32_e32 v96, v0
	v_mov_b32_e32 v97, v0
	v_mov_b32_e32 v98, v0
	v_mov_b32_e32 v99, v0
	v_mov_b32_e32 v120, v0
	v_mov_b32_e32 v121, v0
	v_mov_b32_e32 v122, v0
	v_mov_b32_e32 v123, v0
	v_mov_b32_e32 v112, v0
	v_mov_b32_e32 v113, v0
	v_mov_b32_e32 v114, v0
	v_mov_b32_e32 v115, v0
	v_mov_b32_e32 v76, v0
	v_mov_b32_e32 v77, v0
	v_mov_b32_e32 v78, v0
	v_mov_b32_e32 v79, v0
	v_mov_b32_e32 v72, v0
	v_mov_b32_e32 v73, v0
	v_mov_b32_e32 v74, v0
	v_mov_b32_e32 v75, v0
	v_mov_b32_e32 v92, v0
	v_mov_b32_e32 v93, v0
	v_mov_b32_e32 v94, v0
	v_mov_b32_e32 v95, v0
	v_mov_b32_e32 v88, v0
	v_mov_b32_e32 v89, v0
	v_mov_b32_e32 v90, v0
	v_mov_b32_e32 v91, v0
	v_mov_b32_e32 v108, v0
	v_mov_b32_e32 v109, v0
	v_mov_b32_e32 v110, v0
	v_mov_b32_e32 v111, v0
	v_mov_b32_e32 v104, v0
	v_mov_b32_e32 v105, v0
	v_mov_b32_e32 v106, v0
	v_mov_b32_e32 v107, v0
	v_mov_b32_e32 v124, v0
	v_mov_b32_e32 v125, v0
	v_mov_b32_e32 v126, v0
	v_mov_b32_e32 v127, v0
	v_mov_b32_e32 v116, v0
	v_mov_b32_e32 v117, v0
	v_mov_b32_e32 v118, v0
	v_mov_b32_e32 v119, v0

; template <class Epi, class Sched, bool ALIGN_EPI = false, bool SP2 = false>
; __device__ __forceinline__ void gemm_phase(PG8_LAS unsigned char* lds, const Gemm g, const Sched& S, const Epi& E, int tid_in) {
;     ...
;         for (int t = 0; t < nt; t += 2) {
;             const bool last = (t == nt - 2);
;             const char* a1 = cA + (size_t)(t + 1) * kstep;
;             const char* a2 = last ? nA : cA + (size_t)(t + 2) * kstep; const char* b2 = last ? nB : cB + (size_t)(t + 2) * kstep;
;     ...
;         if (!Epi::DUAL || cur.sel == 1) {
; #pragma unroll
;         for (int a = 0; a < 2; ++a)
; #pragma unroll
;             for (int b = 0; b < 2; ++b)
; #pragma unroll
;                 for (int m = 0; m < 4; ++m)
; #pragma unroll
;                     for (int n = 0; n < 2; ++n) acc[a][b][m][n] = (f32x4){0.f, 0.f, 0.f, 0.f};
;         }
;         cur = nxt; cA = nA; cB = nB; ++ui;
.LBB0_1352:
	v_mov_b64_e32 v[0:1], 0
	v_mov_b64_e32 v[2:3], 0
	v_mov_b64_e32 v[4:5], 0
	v_mov_b64_e32 v[6:7], 0
	v_mov_b64_e32 v[8:9], 0
	v_mov_b64_e32 v[10:11], 0
	v_mov_b64_e32 v[12:13], 0
	v_mov_b64_e32 v[14:15], 0
	v_mov_b64_e32 v[16:17], 0
	v_mov_b64_e32 v[18:19], 0
	v_mov_b64_e32 v[20:21], 0
	v_mov_b64_e32 v[22:23], 0
	v_mov_b64_e32 v[24:25], 0
	v_mov_b64_e32 v[26:27], 0
	v_mov_b64_e32 v[28:29], 0
	v_mov_b64_e32 v[30:31], 0
	v_mov_b64_e32 v[32:33], 0
	v_mov_b64_e32 v[34:35], 0
	v_mov_b64_e32 v[36:37], 0
	v_mov_b64_e32 v[38:39], 0
	v_mov_b64_e32 v[40:41], 0
	v_mov_b64_e32 v[42:43], 0
	v_mov_b64_e32 v[44:45], 0
	v_mov_b64_e32 v[46:47], 0
	v_mov_b64_e32 v[48:49], 0
	v_mov_b64_e32 v[50:51], 0
	v_mov_b64_e32 v[52:53], 0
	v_mov_b64_e32 v[54:55], 0
	v_mov_b64_e32 v[56:57], 0
	v_mov_b64_e32 v[58:59], 0
	v_mov_b64_e32 v[60:61], 0
	v_mov_b64_e32 v[62:63], 0
	v_mov_b64_e32 v[64:65], 0
	v_mov_b64_e32 v[66:67], 0
	v_mov_b64_e32 v[68:69], 0
	v_mov_b64_e32 v[70:71], 0
	v_mov_b64_e32 v[72:73], 0
	v_mov_b64_e32 v[74:75], 0
	v_mov_b64_e32 v[76:77], 0
	v_mov_b64_e32 v[78:79], 0
	v_mov_b64_e32 v[80:81], 0
	v_mov_b64_e32 v[82:83], 0
	v_mov_b64_e32 v[84:85], 0
	v_mov_b64_e32 v[86:87], 0
	v_mov_b64_e32 v[88:89], 0
	v_mov_b64_e32 v[90:91], 0
	v_mov_b64_e32 v[92:93], 0
	v_mov_b64_e32 v[94:95], 0
	v_mov_b64_e32 v[96:97], 0
	v_mov_b64_e32 v[98:99], 0
	v_mov_b64_e32 v[100:101], 0
	v_mov_b64_e32 v[102:103], 0
	v_mov_b64_e32 v[104:105], 0
	v_mov_b64_e32 v[106:107], 0
	v_mov_b64_e32 v[108:109], 0
	v_mov_b64_e32 v[110:111], 0
	v_mov_b64_e32 v[112:113], 0
	v_mov_b64_e32 v[114:115], 0
	v_mov_b64_e32 v[116:117], 0
	v_mov_b64_e32 v[118:119], 0
	v_mov_b64_e32 v[120:121], 0
	v_mov_b64_e32 v[122:123], 0
	v_mov_b64_e32 v[124:125], 0
	v_mov_b64_e32 v[126:127], 0
	s_andn2_b64 vcc, exec, s[20:21]
	s_cbranch_vccnz .LBB0_1355
	s_add_u32 s26, s26, 0x80
	s_addc_u32 s27, s27, 0
	s_add_u32 s51, s28, 0x100
	v_mov_b32_e32 v0, 0
	s_addc_u32 s52, s29, 0
	s_mov_b32 s28, 0
	v_mov_b32_e32 v1, v0
	v_mov_b32_e32 v2, v0
	v_mov_b32_e32 v3, v0
	v_mov_b32_e32 v4, v0
	v_mov_b32_e32 v5, v0
	v_mov_b32_e32 v6, v0
	v_mov_b32_e32 v7, v0
	v_mov_b32_e32 v16, v0
	v_mov_b32_e32 v17, v0
	v_mov_b32_e32 v18, v0
	v_mov_b32_e32 v19, v0
	v_mov_b32_e32 v20, v0
	v_mov_b32_e32 v21, v0
	v_mov_b32_e32 v22, v0
	v_mov_b32_e32 v23, v0
	v_mov_b32_e32 v32, v0
	v_mov_b32_e32 v33, v0
	v_mov_b32_e32 v34, v0
	v_mov_b32_e32 v35, v0
	v_mov_b32_e32 v36, v0
	v_mov_b32_e32 v37, v0
	v_mov_b32_e32 v38, v0
	v_mov_b32_e32 v39, v0
	v_mov_b32_e32 v48, v0
	v_mov_b32_e32 v49, v0
	v_mov_b32_e32 v50, v0
	v_mov_b32_e32 v51, v0
	v_mov_b32_e32 v52, v0
	v_mov_b32_e32 v53, v0
	v_mov_b32_e32 v54, v0
	v_mov_b32_e32 v55, v0
	v_mov_b32_e32 v8, v0
	v_mov_b32_e32 v9, v0
	v_mov_b32_e32 v10, v0
	v_mov_b32_e32 v11, v0
	v_mov_b32_e32 v12, v0
	v_mov_b32_e32 v13, v0
	v_mov_b32_e32 v14, v0
	v_mov_b32_e32 v15, v0
	v_mov_b32_e32 v24, v0
	v_mov_b32_e32 v25, v0
	v_mov_b32_e32 v26, v0
	v_mov_b32_e32 v27, v0
	v_mov_b32_e32 v28, v0
	v_mov_b32_e32 v29, v0
	v_mov_b32_e32 v30, v0
	v_mov_b32_e32 v31, v0
	v_mov_b32_e32 v40, v0
	v_mov_b32_e32 v41, v0
	v_mov_b32_e32 v42, v0
	v_mov_b32_e32 v43, v0
	v_mov_b32_e32 v44, v0
	v_mov_b32_e32 v45, v0
	v_mov_b32_e32 v46, v0
	v_mov_b32_e32 v47, v0
	v_mov_b32_e32 v56, v0
	v_mov_b32_e32 v57, v0
	v_mov_b32_e32 v58, v0
	v_mov_b32_e32 v59, v0
	v_mov_b32_e32 v60, v0
	v_mov_b32_e32 v61, v0
	v_mov_b32_e32 v62, v0
	v_mov_b32_e32 v63, v0
	v_mov_b32_e32 v64, v0
	v_mov_b32_e32 v65, v0
	v_mov_b32_e32 v66, v0
	v_mov_b32_e32 v67, v0
	v_mov_b32_e32 v68, v0
	v_mov_b32_e32 v69, v0
	v_mov_b32_e32 v70, v0
	v_mov_b32_e32 v71, v0
	v_mov_b32_e32 v80, v0
	v_mov_b32_e32 v81, v0
	v_mov_b32_e32 v82, v0
	v_mov_b32_e32 v83, v0
	v_mov_b32_e32 v84, v0
	v_mov_b32_e32 v85, v0
	v_mov_b32_e32 v86, v0
	v_mov_b32_e32 v87, v0
	v_mov_b32_e32 v96, v0
	v_mov_b32_e32 v97, v0
	v_mov_b32_e32 v98, v0
	v_mov_b32_e32 v99, v0
	v_mov_b32_e32 v100, v0
	v_mov_b32_e32 v101, v0
	v_mov_b32_e32 v102, v0
	v_mov_b32_e32 v103, v0
	v_mov_b32_e32 v112, v0
	v_mov_b32_e32 v113, v0
	v_mov_b32_e32 v114, v0
	v_mov_b32_e32 v115, v0
	v_mov_b32_e32 v116, v0
	v_mov_b32_e32 v117, v0
	v_mov_b32_e32 v118, v0
	v_mov_b32_e32 v119, v0
	v_mov_b32_e32 v72, v0
	v_mov_b32_e32 v73, v0
	v_mov_b32_e32 v74, v0
	v_mov_b32_e32 v75, v0
	v_mov_b32_e32 v76, v0
	v_mov_b32_e32 v77, v0
	v_mov_b32_e32 v78, v0
	v_mov_b32_e32 v79, v0
	v_mov_b32_e32 v88, v0
	v_mov_b32_e32 v89, v0
	v_mov_b32_e32 v90, v0
	v_mov_b32_e32 v91, v0
	v_mov_b32_e32 v92, v0
	v_mov_b32_e32 v93, v0
	v_mov_b32_e32 v94, v0
	v_mov_b32_e32 v95, v0
	v_mov_b32_e32 v104, v0
	v_mov_b32_e32 v105, v0
	v_mov_b32_e32 v106, v0
	v_mov_b32_e32 v107, v0
	v_mov_b32_e32 v108, v0
	v_mov_b32_e32 v109, v0
	v_mov_b32_e32 v110, v0
	v_mov_b32_e32 v111, v0
	v_mov_b32_e32 v124, v0
	v_mov_b32_e32 v125, v0
	v_mov_b32_e32 v126, v0
	v_mov_b32_e32 v127, v0
	v_mov_b32_e32 v120, v0
	v_mov_b32_e32 v121, v0
	v_mov_b32_e32 v122, v0
	v_mov_b32_e32 v123, v0

; template <class Epi, class Sched, bool ALIGN_EPI = false, bool SP2 = false>
; __device__ __forceinline__ void gemm_phase(PG8_LAS unsigned char* lds, const Gemm g, const Sched& S, const Epi& E, int tid_in) {
;     ...
;         for (int t = 0; t < nt; t += 2) {
;             const bool last = (t == nt - 2);
;             const char* a1 = cA + (size_t)(t + 1) * kstep;
;             const char* a2 = last ? nA : cA + (size_t)(t + 2) * kstep; const char* b2 = last ? nB : cB + (size_t)(t + 2) * kstep;
;     ...
;         if (!Epi::DUAL || cur.sel == 1) {
; #pragma unroll
;         for (int a = 0; a < 2; ++a)
; #pragma unroll
;             for (int b = 0; b < 2; ++b)
; #pragma unroll
;                 for (int m = 0; m < 4; ++m)
; #pragma unroll
;                     for (int n = 0; n < 2; ++n) acc[a][b][m][n] = (f32x4){0.f, 0.f, 0.f, 0.f};
;         }
;         cur = nxt; cA = nA; cB = nB; ++ui;
.LBB0_1445:
	v_mov_b64_e32 v[0:1], 0
	v_mov_b64_e32 v[2:3], 0
	v_mov_b64_e32 v[4:5], 0
	v_mov_b64_e32 v[6:7], 0
	v_mov_b64_e32 v[8:9], 0
	v_mov_b64_e32 v[10:11], 0
	v_mov_b64_e32 v[12:13], 0
	v_mov_b64_e32 v[14:15], 0
	v_mov_b64_e32 v[16:17], 0
	v_mov_b64_e32 v[18:19], 0
	v_mov_b64_e32 v[20:21], 0
	v_mov_b64_e32 v[22:23], 0
	v_mov_b64_e32 v[24:25], 0
	v_mov_b64_e32 v[26:27], 0
	v_mov_b64_e32 v[28:29], 0
	v_mov_b64_e32 v[30:31], 0
	v_mov_b64_e32 v[32:33], 0
	v_mov_b64_e32 v[34:35], 0
	v_mov_b64_e32 v[36:37], 0
	v_mov_b64_e32 v[38:39], 0
	v_mov_b64_e32 v[40:41], 0
	v_mov_b64_e32 v[42:43], 0
	v_mov_b64_e32 v[44:45], 0
	v_mov_b64_e32 v[46:47], 0
	v_mov_b64_e32 v[48:49], 0
	v_mov_b64_e32 v[50:51], 0
	v_mov_b64_e32 v[52:53], 0
	v_mov_b64_e32 v[54:55], 0
	v_mov_b64_e32 v[56:57], 0
	v_mov_b64_e32 v[58:59], 0
	v_mov_b64_e32 v[60:61], 0
	v_mov_b64_e32 v[62:63], 0
	v_mov_b64_e32 v[64:65], 0
	v_mov_b64_e32 v[66:67], 0
	v_mov_b64_e32 v[68:69], 0
	v_mov_b64_e32 v[70:71], 0
	v_mov_b64_e32 v[72:73], 0
	v_mov_b64_e32 v[74:75], 0
	v_mov_b64_e32 v[76:77], 0
	v_mov_b64_e32 v[78:79], 0
	v_mov_b64_e32 v[80:81], 0
	v_mov_b64_e32 v[82:83], 0
	v_mov_b64_e32 v[84:85], 0
	v_mov_b64_e32 v[86:87], 0
	v_mov_b64_e32 v[88:89], 0
	v_mov_b64_e32 v[90:91], 0
	v_mov_b64_e32 v[92:93], 0
	v_mov_b64_e32 v[94:95], 0
	v_mov_b64_e32 v[96:97], 0
	v_mov_b64_e32 v[98:99], 0
	v_mov_b64_e32 v[100:101], 0
	v_mov_b64_e32 v[102:103], 0
	v_mov_b64_e32 v[104:105], 0
	v_mov_b64_e32 v[106:107], 0
	v_mov_b64_e32 v[108:109], 0
	v_mov_b64_e32 v[110:111], 0
	v_mov_b64_e32 v[112:113], 0
	v_mov_b64_e32 v[114:115], 0
	v_mov_b64_e32 v[116:117], 0
	v_mov_b64_e32 v[118:119], 0
	v_mov_b64_e32 v[120:121], 0
	v_mov_b64_e32 v[122:123], 0
	v_mov_b64_e32 v[124:125], 0
	v_mov_b64_e32 v[126:127], 0
	s_and_b64 vcc, exec, s[6:7]
	s_cbranch_vccnz .LBB0_1448
	s_add_u32 s26, s26, 0x80
	s_addc_u32 s27, s27, 0
	s_add_u32 s53, s30, 0x100
	v_mov_b32_e32 v0, 0
	s_addc_u32 s54, s31, 0
	s_mov_b32 s30, 0
	v_mov_b32_e32 v1, v0
	v_mov_b32_e32 v2, v0
	v_mov_b32_e32 v3, v0
	v_mov_b32_e32 v4, v0
	v_mov_b32_e32 v5, v0
	v_mov_b32_e32 v6, v0
	v_mov_b32_e32 v7, v0
	v_mov_b32_e32 v16, v0
	v_mov_b32_e32 v17, v0
	v_mov_b32_e32 v18, v0
	v_mov_b32_e32 v19, v0
	v_mov_b32_e32 v20, v0
	v_mov_b32_e32 v21, v0
	v_mov_b32_e32 v22, v0
	v_mov_b32_e32 v23, v0
	v_mov_b32_e32 v32, v0
	v_mov_b32_e32 v33, v0
	v_mov_b32_e32 v34, v0
	v_mov_b32_e32 v35, v0
	v_mov_b32_e32 v36, v0
	v_mov_b32_e32 v37, v0
	v_mov_b32_e32 v38, v0
	v_mov_b32_e32 v39, v0
	v_mov_b32_e32 v48, v0
	v_mov_b32_e32 v49, v0
	v_mov_b32_e32 v50, v0
	v_mov_b32_e32 v51, v0
	v_mov_b32_e32 v52, v0
	v_mov_b32_e32 v53, v0
	v_mov_b32_e32 v54, v0
	v_mov_b32_e32 v55, v0
	v_mov_b32_e32 v8, v0
	v_mov_b32_e32 v9, v0
	v_mov_b32_e32 v10, v0
	v_mov_b32_e32 v11, v0
	v_mov_b32_e32 v12, v0
	v_mov_b32_e32 v13, v0
	v_mov_b32_e32 v14, v0
	v_mov_b32_e32 v15, v0
	v_mov_b32_e32 v24, v0
	v_mov_b32_e32 v25, v0
	v_mov_b32_e32 v26, v0
	v_mov_b32_e32 v27, v0
	v_mov_b32_e32 v28, v0
	v_mov_b32_e32 v29, v0
	v_mov_b32_e32 v30, v0
	v_mov_b32_e32 v31, v0
	v_mov_b32_e32 v40, v0
	v_mov_b32_e32 v41, v0
	v_mov_b32_e32 v42, v0
	v_mov_b32_e32 v43, v0
	v_mov_b32_e32 v44, v0
	v_mov_b32_e32 v45, v0
	v_mov_b32_e32 v46, v0
	v_mov_b32_e32 v47, v0
	v_mov_b32_e32 v56, v0
	v_mov_b32_e32 v57, v0
	v_mov_b32_e32 v58, v0
	v_mov_b32_e32 v59, v0
	v_mov_b32_e32 v60, v0
	v_mov_b32_e32 v61, v0
	v_mov_b32_e32 v62, v0
	v_mov_b32_e32 v63, v0
	v_mov_b32_e32 v64, v0
	v_mov_b32_e32 v65, v0
	v_mov_b32_e32 v66, v0
	v_mov_b32_e32 v67, v0
	v_mov_b32_e32 v68, v0
	v_mov_b32_e32 v69, v0
	v_mov_b32_e32 v70, v0
	v_mov_b32_e32 v71, v0
	v_mov_b32_e32 v80, v0
	v_mov_b32_e32 v81, v0
	v_mov_b32_e32 v82, v0
	v_mov_b32_e32 v83, v0
	v_mov_b32_e32 v84, v0
	v_mov_b32_e32 v85, v0
	v_mov_b32_e32 v86, v0
	v_mov_b32_e32 v87, v0
	v_mov_b32_e32 v96, v0
	v_mov_b32_e32 v97, v0
	v_mov_b32_e32 v98, v0
	v_mov_b32_e32 v99, v0
	v_mov_b32_e32 v100, v0
	v_mov_b32_e32 v101, v0
	v_mov_b32_e32 v102, v0
	v_mov_b32_e32 v103, v0
	v_mov_b32_e32 v112, v0
	v_mov_b32_e32 v113, v0
	v_mov_b32_e32 v114, v0
	v_mov_b32_e32 v115, v0
	v_mov_b32_e32 v116, v0
	v_mov_b32_e32 v117, v0
	v_mov_b32_e32 v118, v0
	v_mov_b32_e32 v119, v0
	v_mov_b32_e32 v72, v0
	v_mov_b32_e32 v73, v0
	v_mov_b32_e32 v74, v0
	v_mov_b32_e32 v75, v0
	v_mov_b32_e32 v76, v0
	v_mov_b32_e32 v77, v0
	v_mov_b32_e32 v78, v0
	v_mov_b32_e32 v79, v0
	v_mov_b32_e32 v88, v0
	v_mov_b32_e32 v89, v0
	v_mov_b32_e32 v90, v0
	v_mov_b32_e32 v91, v0
	v_mov_b32_e32 v92, v0
	v_mov_b32_e32 v93, v0
	v_mov_b32_e32 v94, v0
	v_mov_b32_e32 v95, v0
	v_mov_b32_e32 v104, v0
	v_mov_b32_e32 v105, v0
	v_mov_b32_e32 v106, v0
	v_mov_b32_e32 v107, v0
	v_mov_b32_e32 v108, v0
	v_mov_b32_e32 v109, v0
	v_mov_b32_e32 v110, v0
	v_mov_b32_e32 v111, v0
	v_mov_b32_e32 v120, v0
	v_mov_b32_e32 v121, v0
	v_mov_b32_e32 v122, v0
	v_mov_b32_e32 v123, v0
	v_mov_b32_e32 v124, v0
	v_mov_b32_e32 v125, v0
	v_mov_b32_e32 v126, v0
	v_mov_b32_e32 v127, v0

; template <class Epi, class Sched, bool ALIGN_EPI = false, bool SP2 = false>
; __device__ __forceinline__ void gemm_phase(PG8_LAS unsigned char* lds, const Gemm g, const Sched& S, const Epi& E, int tid_in) {
;     ...
;         for (int t = 0; t < nt; t += 2) {
;             const bool last = (t == nt - 2);
;             const char* a1 = cA + (size_t)(t + 1) * kstep;
;             const char* a2 = last ? nA : cA + (size_t)(t + 2) * kstep; const char* b2 = last ? nB : cB + (size_t)(t + 2) * kstep;
;     ...
;         if (!Epi::DUAL || cur.sel == 1) {
; #pragma unroll
;         for (int a = 0; a < 2; ++a)
; #pragma unroll
;             for (int b = 0; b < 2; ++b)
; #pragma unroll
;                 for (int m = 0; m < 4; ++m)
; #pragma unroll
;                     for (int n = 0; n < 2; ++n) acc[a][b][m][n] = (f32x4){0.f, 0.f, 0.f, 0.f};
;         }
;         cur = nxt; cA = nA; cB = nB; ++ui;
.LBB0_1466:
	v_mov_b64_e32 v[0:1], 0
	v_mov_b64_e32 v[2:3], 0
	v_mov_b64_e32 v[4:5], 0
	v_mov_b64_e32 v[6:7], 0
	v_mov_b64_e32 v[8:9], 0
	v_mov_b64_e32 v[10:11], 0
	v_mov_b64_e32 v[12:13], 0
	v_mov_b64_e32 v[14:15], 0
	v_mov_b64_e32 v[16:17], 0
	v_mov_b64_e32 v[18:19], 0
	v_mov_b64_e32 v[20:21], 0
	v_mov_b64_e32 v[22:23], 0
	v_mov_b64_e32 v[24:25], 0
	v_mov_b64_e32 v[26:27], 0
	v_mov_b64_e32 v[28:29], 0
	v_mov_b64_e32 v[30:31], 0
	v_mov_b64_e32 v[32:33], 0
	v_mov_b64_e32 v[34:35], 0
	v_mov_b64_e32 v[36:37], 0
	v_mov_b64_e32 v[38:39], 0
	v_mov_b64_e32 v[40:41], 0
	v_mov_b64_e32 v[42:43], 0
	v_mov_b64_e32 v[44:45], 0
	v_mov_b64_e32 v[46:47], 0
	v_mov_b64_e32 v[48:49], 0
	v_mov_b64_e32 v[50:51], 0
	v_mov_b64_e32 v[52:53], 0
	v_mov_b64_e32 v[54:55], 0
	v_mov_b64_e32 v[56:57], 0
	v_mov_b64_e32 v[58:59], 0
	v_mov_b64_e32 v[60:61], 0
	v_mov_b64_e32 v[62:63], 0
	v_mov_b64_e32 v[64:65], 0
	v_mov_b64_e32 v[66:67], 0
	v_mov_b64_e32 v[68:69], 0
	v_mov_b64_e32 v[70:71], 0
	v_mov_b64_e32 v[72:73], 0
	v_mov_b64_e32 v[74:75], 0
	v_mov_b64_e32 v[76:77], 0
	v_mov_b64_e32 v[78:79], 0
	v_mov_b64_e32 v[80:81], 0
	v_mov_b64_e32 v[82:83], 0
	v_mov_b64_e32 v[84:85], 0
	v_mov_b64_e32 v[86:87], 0
	v_mov_b64_e32 v[88:89], 0
	v_mov_b64_e32 v[90:91], 0
	v_mov_b64_e32 v[92:93], 0
	v_mov_b64_e32 v[94:95], 0
	v_mov_b64_e32 v[96:97], 0
	v_mov_b64_e32 v[98:99], 0
	v_mov_b64_e32 v[100:101], 0
	v_mov_b64_e32 v[102:103], 0
	v_mov_b64_e32 v[104:105], 0
	v_mov_b64_e32 v[106:107], 0
	v_mov_b64_e32 v[108:109], 0
	v_mov_b64_e32 v[110:111], 0
	v_mov_b64_e32 v[112:113], 0
	v_mov_b64_e32 v[114:115], 0
	v_mov_b64_e32 v[116:117], 0
	v_mov_b64_e32 v[118:119], 0
	v_mov_b64_e32 v[120:121], 0
	v_mov_b64_e32 v[122:123], 0
	v_mov_b64_e32 v[124:125], 0
	v_mov_b64_e32 v[126:127], 0
	s_andn2_b64 vcc, exec, s[24:25]
	s_cbranch_vccnz .LBB0_1469
	s_add_u32 s30, s30, 0x80
	s_addc_u32 s31, s31, 0
	s_add_u32 s33, s34, 0x100
	v_mov_b32_e32 v0, 0
	s_addc_u32 s54, s35, 0
	s_mov_b32 s34, 0
	v_mov_b32_e32 v1, v0
	v_mov_b32_e32 v2, v0
	v_mov_b32_e32 v3, v0
	v_mov_b32_e32 v4, v0
	v_mov_b32_e32 v5, v0
	v_mov_b32_e32 v6, v0
	v_mov_b32_e32 v7, v0
	v_mov_b32_e32 v16, v0
	v_mov_b32_e32 v17, v0
	v_mov_b32_e32 v18, v0
	v_mov_b32_e32 v19, v0
	v_mov_b32_e32 v20, v0
	v_mov_b32_e32 v21, v0
	v_mov_b32_e32 v22, v0
	v_mov_b32_e32 v23, v0
	v_mov_b32_e32 v32, v0
	v_mov_b32_e32 v33, v0
	v_mov_b32_e32 v34, v0
	v_mov_b32_e32 v35, v0
	v_mov_b32_e32 v36, v0
	v_mov_b32_e32 v37, v0
	v_mov_b32_e32 v38, v0
	v_mov_b32_e32 v39, v0
	v_mov_b32_e32 v48, v0
	v_mov_b32_e32 v49, v0
	v_mov_b32_e32 v50, v0
	v_mov_b32_e32 v51, v0
	v_mov_b32_e32 v52, v0
	v_mov_b32_e32 v53, v0
	v_mov_b32_e32 v54, v0
	v_mov_b32_e32 v55, v0
	v_mov_b32_e32 v8, v0
	v_mov_b32_e32 v9, v0
	v_mov_b32_e32 v10, v0
	v_mov_b32_e32 v11, v0
	v_mov_b32_e32 v12, v0
	v_mov_b32_e32 v13, v0
	v_mov_b32_e32 v14, v0
	v_mov_b32_e32 v15, v0
	v_mov_b32_e32 v24, v0
	v_mov_b32_e32 v25, v0
	v_mov_b32_e32 v26, v0
	v_mov_b32_e32 v27, v0
	v_mov_b32_e32 v28, v0
	v_mov_b32_e32 v29, v0
	v_mov_b32_e32 v30, v0
	v_mov_b32_e32 v31, v0
	v_mov_b32_e32 v40, v0
	v_mov_b32_e32 v41, v0
	v_mov_b32_e32 v42, v0
	v_mov_b32_e32 v43, v0
	v_mov_b32_e32 v44, v0
	v_mov_b32_e32 v45, v0
	v_mov_b32_e32 v46, v0
	v_mov_b32_e32 v47, v0
	v_mov_b32_e32 v56, v0
	v_mov_b32_e32 v57, v0
	v_mov_b32_e32 v58, v0
	v_mov_b32_e32 v59, v0
	v_mov_b32_e32 v60, v0
	v_mov_b32_e32 v61, v0
	v_mov_b32_e32 v62, v0
	v_mov_b32_e32 v63, v0
	v_mov_b32_e32 v64, v0
	v_mov_b32_e32 v65, v0
	v_mov_b32_e32 v66, v0
	v_mov_b32_e32 v67, v0
	v_mov_b32_e32 v68, v0
	v_mov_b32_e32 v69, v0
	v_mov_b32_e32 v70, v0
	v_mov_b32_e32 v71, v0
	v_mov_b32_e32 v80, v0
	v_mov_b32_e32 v81, v0
	v_mov_b32_e32 v82, v0
	v_mov_b32_e32 v83, v0
	v_mov_b32_e32 v84, v0
	v_mov_b32_e32 v85, v0
	v_mov_b32_e32 v86, v0
	v_mov_b32_e32 v87, v0
	v_mov_b32_e32 v96, v0
	v_mov_b32_e32 v97, v0
	v_mov_b32_e32 v98, v0
	v_mov_b32_e32 v99, v0
	v_mov_b32_e32 v100, v0
	v_mov_b32_e32 v101, v0
	v_mov_b32_e32 v102, v0
	v_mov_b32_e32 v103, v0
	v_mov_b32_e32 v112, v0
	v_mov_b32_e32 v113, v0
	v_mov_b32_e32 v114, v0
	v_mov_b32_e32 v115, v0
	v_mov_b32_e32 v116, v0
	v_mov_b32_e32 v117, v0
	v_mov_b32_e32 v118, v0
	v_mov_b32_e32 v119, v0
	v_mov_b32_e32 v72, v0
	v_mov_b32_e32 v73, v0
	v_mov_b32_e32 v74, v0
	v_mov_b32_e32 v75, v0
	v_mov_b32_e32 v76, v0
	v_mov_b32_e32 v77, v0
	v_mov_b32_e32 v78, v0
	v_mov_b32_e32 v79, v0
	v_mov_b32_e32 v88, v0
	v_mov_b32_e32 v89, v0
	v_mov_b32_e32 v90, v0
	v_mov_b32_e32 v91, v0
	v_mov_b32_e32 v92, v0
	v_mov_b32_e32 v93, v0
	v_mov_b32_e32 v94, v0
	v_mov_b32_e32 v95, v0
	v_mov_b32_e32 v104, v0
	v_mov_b32_e32 v105, v0
	v_mov_b32_e32 v106, v0
	v_mov_b32_e32 v107, v0
	v_mov_b32_e32 v108, v0
	v_mov_b32_e32 v109, v0
	v_mov_b32_e32 v110, v0
	v_mov_b32_e32 v111, v0
	v_mov_b32_e32 v120, v0
	v_mov_b32_e32 v121, v0
	v_mov_b32_e32 v122, v0
	v_mov_b32_e32 v123, v0
	v_mov_b32_e32 v124, v0
	v_mov_b32_e32 v125, v0
	v_mov_b32_e32 v126, v0
	v_mov_b32_e32 v127, v0
